# write-through sc1 also on the XCD-local epilogue stores (residual XB, gate T / merged, row sum-of-squares); on top of v28
# baseline (speedup 1.0000x reference)
; __device__ __forceinline__ float bflo(unsigned w) { return __uint_as_float(w << 16); }
; __device__ __forceinline__ float bfhi(unsigned w) { return __uint_as_float(w & 0xffff0000u); }
; __device__ __forceinline__ u32x4 pack8(const f32x4 a, const f32x4 b) { u32x4 w; w.x = cvt_pk_bf16(a[0], a[1]); w.y = cvt_pk_bf16(a[2], a[3]); w.z = cvt_pk_bf16(b[0], b[1]); w.w = cvt_pk_bf16(b[2], b[3]); return w; }
;     __device__ __forceinline__ void operator()(const f32x4 (&acc)[2][2][4][2], const Unit& u, int wr, int wc, int fr, int fq) const {
;         const int row0 = u.pm * 256 + wr * 64 + fr, col0 = u.pn * 256 + wc * 32 + 8 * fq;
; #pragma unroll
;         for (int ai = 0; ai < 2; ++ai)
; #pragma unroll
;             for (int m = 0; m < 4; ++m) {
;                 const int row = row0 + ai * 128 + m * 16; float p = 0.f;
; #pragma unroll
;                 for (int bj = 0; bj < 2; ++bj) {
;                     const size_t off = (size_t)row * D + col0 + bj * 128;
;                     const u32x4 xx = *(const u32x4*)(xb + off);
;                     const f32x4 x0 = (f32x4){bflo(xx.x), bfhi(xx.x), bflo(xx.y), bfhi(xx.y)}, x1 = (f32x4){bflo(xx.z), bfhi(xx.z), bflo(xx.w), bfhi(xx.w)};
;                     const f32x4 y0 = x0 + acc[ai][bj][m][0] * scale, y1 = x1 + acc[ai][bj][m][1] * scale;
;                     *(u32x4*)(xb + off) = pack8(y0, y1);
;                     const f32x4 q = y0 * y0 + y1 * y1; p += (q[0] + q[1]) + (q[2] + q[3]);
;                 }
;                 p += __shfl_xor(p, 16); p += __shfl_xor(p, 32);
;                 if (fq == 0) ssn[(size_t)row * 16 + u.pn * 4 + wc] = p;
;             }
.LBB0_365:
	s_waitcnt vmcnt(15)
	v_lshlrev_b32_e32 v144, 16, v152
	v_and_b32_e32 v145, 0xffff0000, v152
	v_lshlrev_b32_e32 v146, 16, v153
	v_and_b32_e32 v147, 0xffff0000, v153
	v_pk_fma_f32 v[126:127], v[126:127], 0.5, v[144:145] op_sel_hi:[1,0,1]
	v_pk_fma_f32 v[128:129], v[128:129], 0.5, v[146:147] op_sel_hi:[1,0,1]
	v_lshlrev_b32_e32 v144, 16, v154
	v_and_b32_e32 v145, 0xffff0000, v154
	v_lshlrev_b32_e32 v146, 16, v155
	v_and_b32_e32 v147, 0xffff0000, v155
	v_pk_fma_f32 v[122:123], v[122:123], 0.5, v[144:145] op_sel_hi:[1,0,1]
	v_pk_fma_f32 v[124:125], v[124:125], 0.5, v[146:147] op_sel_hi:[1,0,1]
	v_cvt_pk_bf16_f32 v152, v126, v127
	v_cvt_pk_bf16_f32 v153, v128, v129
	v_cvt_pk_bf16_f32 v154, v122, v123
	v_cvt_pk_bf16_f32 v155, v124, v125
	global_store_dwordx4 v138, v[152:155], s[34:35] sc1
	v_pk_mul_f32 v[126:127], v[126:127], v[126:127]
	v_pk_fma_f32 v[126:127], v[128:129], v[128:129], v[126:127]
	v_pk_fma_f32 v[126:127], v[122:123], v[122:123], v[126:127]
	v_pk_fma_f32 v[126:127], v[124:125], v[124:125], v[126:127]
	s_waitcnt vmcnt(15)
	v_lshlrev_b32_e32 v144, 16, v156
	v_and_b32_e32 v145, 0xffff0000, v156
	v_lshlrev_b32_e32 v146, 16, v157
	v_and_b32_e32 v147, 0xffff0000, v157
	v_pk_fma_f32 v[118:119], v[118:119], 0.5, v[144:145] op_sel_hi:[1,0,1]
	v_pk_fma_f32 v[120:121], v[120:121], 0.5, v[146:147] op_sel_hi:[1,0,1]
	v_lshlrev_b32_e32 v144, 16, v158
	v_and_b32_e32 v145, 0xffff0000, v158
	v_lshlrev_b32_e32 v146, 16, v159
	v_and_b32_e32 v147, 0xffff0000, v159
	v_pk_fma_f32 v[114:115], v[114:115], 0.5, v[144:145] op_sel_hi:[1,0,1]
	v_pk_fma_f32 v[116:117], v[116:117], 0.5, v[146:147] op_sel_hi:[1,0,1]
	v_cvt_pk_bf16_f32 v156, v118, v119
	v_cvt_pk_bf16_f32 v157, v120, v121
	v_cvt_pk_bf16_f32 v158, v114, v115
	v_cvt_pk_bf16_f32 v159, v116, v117
	global_store_dwordx4 v138, v[156:159], s[34:35] offset:256 sc1
	v_pk_fma_f32 v[126:127], v[118:119], v[118:119], v[126:127]
	v_pk_fma_f32 v[126:127], v[120:121], v[120:121], v[126:127]
	v_pk_fma_f32 v[126:127], v[114:115], v[114:115], v[126:127]
	v_pk_fma_f32 v[126:127], v[116:117], v[116:117], v[126:127]
	v_add_f32_e32 v126, v126, v127
	v_add_u32_e32 v139, 0x8000, v138
	s_waitcnt vmcnt(15)
	v_lshlrev_b32_e32 v144, 16, v160
	v_and_b32_e32 v145, 0xffff0000, v160
	v_lshlrev_b32_e32 v146, 16, v161
	v_and_b32_e32 v147, 0xffff0000, v161
	v_pk_fma_f32 v[110:111], v[110:111], 0.5, v[144:145] op_sel_hi:[1,0,1]
	v_pk_fma_f32 v[112:113], v[112:113], 0.5, v[146:147] op_sel_hi:[1,0,1]
	v_lshlrev_b32_e32 v144, 16, v162
	v_and_b32_e32 v145, 0xffff0000, v162
	v_lshlrev_b32_e32 v146, 16, v163
	v_and_b32_e32 v147, 0xffff0000, v163
	v_pk_fma_f32 v[106:107], v[106:107], 0.5, v[144:145] op_sel_hi:[1,0,1]
	v_pk_fma_f32 v[108:109], v[108:109], 0.5, v[146:147] op_sel_hi:[1,0,1]
	v_cvt_pk_bf16_f32 v160, v110, v111
	v_cvt_pk_bf16_f32 v161, v112, v113
	v_cvt_pk_bf16_f32 v162, v106, v107
	v_cvt_pk_bf16_f32 v163, v108, v109
	global_store_dwordx4 v139, v[160:163], s[34:35] sc1
	v_pk_mul_f32 v[110:111], v[110:111], v[110:111]
	v_pk_fma_f32 v[110:111], v[112:113], v[112:113], v[110:111]
	v_pk_fma_f32 v[110:111], v[106:107], v[106:107], v[110:111]
	v_pk_fma_f32 v[110:111], v[108:109], v[108:109], v[110:111]
	s_waitcnt vmcnt(15)
	v_lshlrev_b32_e32 v144, 16, v164
	v_and_b32_e32 v145, 0xffff0000, v164
	v_lshlrev_b32_e32 v146, 16, v165
	v_and_b32_e32 v147, 0xffff0000, v165
	v_pk_fma_f32 v[102:103], v[102:103], 0.5, v[144:145] op_sel_hi:[1,0,1]
	v_pk_fma_f32 v[104:105], v[104:105], 0.5, v[146:147] op_sel_hi:[1,0,1]
	v_lshlrev_b32_e32 v144, 16, v166
	v_and_b32_e32 v145, 0xffff0000, v166
	v_lshlrev_b32_e32 v146, 16, v167
	v_and_b32_e32 v147, 0xffff0000, v167
	v_pk_fma_f32 v[98:99], v[98:99], 0.5, v[144:145] op_sel_hi:[1,0,1]
	v_pk_fma_f32 v[100:101], v[100:101], 0.5, v[146:147] op_sel_hi:[1,0,1]
	v_cvt_pk_bf16_f32 v164, v102, v103
	v_cvt_pk_bf16_f32 v165, v104, v105
	v_cvt_pk_bf16_f32 v166, v98, v99
	v_cvt_pk_bf16_f32 v167, v100, v101
	global_store_dwordx4 v139, v[164:167], s[34:35] offset:256 sc1
	v_pk_fma_f32 v[110:111], v[102:103], v[102:103], v[110:111]
	v_pk_fma_f32 v[110:111], v[104:105], v[104:105], v[110:111]
	v_pk_fma_f32 v[110:111], v[98:99], v[98:99], v[110:111]
	v_pk_fma_f32 v[110:111], v[100:101], v[100:101], v[110:111]
	v_add_f32_e32 v110, v110, v111
	v_add_u32_e32 v139, 0x10000, v138
	s_waitcnt vmcnt(15)
	v_lshlrev_b32_e32 v144, 16, v168
	v_and_b32_e32 v145, 0xffff0000, v168
	v_lshlrev_b32_e32 v146, 16, v169
	v_and_b32_e32 v147, 0xffff0000, v169
	v_pk_fma_f32 v[94:95], v[94:95], 0.5, v[144:145] op_sel_hi:[1,0,1]
	v_pk_fma_f32 v[96:97], v[96:97], 0.5, v[146:147] op_sel_hi:[1,0,1]
	v_lshlrev_b32_e32 v144, 16, v170
	v_and_b32_e32 v145, 0xffff0000, v170
	v_lshlrev_b32_e32 v146, 16, v171
	v_and_b32_e32 v147, 0xffff0000, v171
	v_pk_fma_f32 v[90:91], v[90:91], 0.5, v[144:145] op_sel_hi:[1,0,1]
	v_pk_fma_f32 v[92:93], v[92:93], 0.5, v[146:147] op_sel_hi:[1,0,1]
	v_cvt_pk_bf16_f32 v168, v94, v95
	v_cvt_pk_bf16_f32 v169, v96, v97
	v_cvt_pk_bf16_f32 v170, v90, v91
	v_cvt_pk_bf16_f32 v171, v92, v93
	global_store_dwordx4 v139, v[168:171], s[34:35] sc1
	v_pk_mul_f32 v[94:95], v[94:95], v[94:95]
	v_pk_fma_f32 v[94:95], v[96:97], v[96:97], v[94:95]
	v_pk_fma_f32 v[94:95], v[90:91], v[90:91], v[94:95]
	v_pk_fma_f32 v[94:95], v[92:93], v[92:93], v[94:95]
	s_waitcnt vmcnt(15)
; __device__ __forceinline__ float bflo(unsigned w) { return __uint_as_float(w << 16); }
; __device__ __forceinline__ float bfhi(unsigned w) { return __uint_as_float(w & 0xffff0000u); }
; __device__ __forceinline__ u32x4 pack8(const f32x4 a, const f32x4 b) { u32x4 w; w.x = cvt_pk_bf16(a[0], a[1]); w.y = cvt_pk_bf16(a[2], a[3]); w.z = cvt_pk_bf16(b[0], b[1]); w.w = cvt_pk_bf16(b[2], b[3]); return w; }
;     __device__ __forceinline__ void operator()(const f32x4 (&acc)[2][2][4][2], const Unit& u, int wr, int wc, int fr, int fq) const {
;         const int row0 = u.pm * 256 + wr * 64 + fr, col0 = u.pn * 256 + wc * 32 + 8 * fq;
; #pragma unroll
;         for (int ai = 0; ai < 2; ++ai)
; #pragma unroll
;             for (int m = 0; m < 4; ++m) {
;                 const int row = row0 + ai * 128 + m * 16; float p = 0.f;
; #pragma unroll
;                 for (int bj = 0; bj < 2; ++bj) {
;                     const size_t off = (size_t)row * D + col0 + bj * 128;
;                     const u32x4 xx = *(const u32x4*)(xb + off);
;                     const f32x4 x0 = (f32x4){bflo(xx.x), bfhi(xx.x), bflo(xx.y), bfhi(xx.y)}, x1 = (f32x4){bflo(xx.z), bfhi(xx.z), bflo(xx.w), bfhi(xx.w)};
;                     const f32x4 y0 = x0 + acc[ai][bj][m][0] * scale, y1 = x1 + acc[ai][bj][m][1] * scale;
;                     *(u32x4*)(xb + off) = pack8(y0, y1);
;                     const f32x4 q = y0 * y0 + y1 * y1; p += (q[0] + q[1]) + (q[2] + q[3]);
;                 }
;                 p += __shfl_xor(p, 16); p += __shfl_xor(p, 32);
;                 if (fq == 0) ssn[(size_t)row * 16 + u.pn * 4 + wc] = p;
;             }
	v_lshlrev_b32_e32 v144, 16, v172
	v_and_b32_e32 v145, 0xffff0000, v172
	v_lshlrev_b32_e32 v146, 16, v173
	v_and_b32_e32 v147, 0xffff0000, v173
	v_pk_fma_f32 v[86:87], v[86:87], 0.5, v[144:145] op_sel_hi:[1,0,1]
	v_pk_fma_f32 v[88:89], v[88:89], 0.5, v[146:147] op_sel_hi:[1,0,1]
	v_lshlrev_b32_e32 v144, 16, v174
	v_and_b32_e32 v145, 0xffff0000, v174
	v_lshlrev_b32_e32 v146, 16, v175
	v_and_b32_e32 v147, 0xffff0000, v175
	v_pk_fma_f32 v[82:83], v[82:83], 0.5, v[144:145] op_sel_hi:[1,0,1]
	v_pk_fma_f32 v[84:85], v[84:85], 0.5, v[146:147] op_sel_hi:[1,0,1]
	v_cvt_pk_bf16_f32 v172, v86, v87
	v_cvt_pk_bf16_f32 v173, v88, v89
	v_cvt_pk_bf16_f32 v174, v82, v83
	v_cvt_pk_bf16_f32 v175, v84, v85
	global_store_dwordx4 v139, v[172:175], s[34:35] offset:256 sc1
	v_pk_fma_f32 v[94:95], v[86:87], v[86:87], v[94:95]
	v_pk_fma_f32 v[94:95], v[88:89], v[88:89], v[94:95]
	v_pk_fma_f32 v[94:95], v[82:83], v[82:83], v[94:95]
	v_pk_fma_f32 v[94:95], v[84:85], v[84:85], v[94:95]
	v_add_f32_e32 v94, v94, v95
	v_add_u32_e32 v139, 0x18000, v138
	s_waitcnt vmcnt(15)
	v_lshlrev_b32_e32 v144, 16, v176
	v_and_b32_e32 v145, 0xffff0000, v176
	v_lshlrev_b32_e32 v146, 16, v177
	v_and_b32_e32 v147, 0xffff0000, v177
	v_pk_fma_f32 v[78:79], v[78:79], 0.5, v[144:145] op_sel_hi:[1,0,1]
	v_pk_fma_f32 v[80:81], v[80:81], 0.5, v[146:147] op_sel_hi:[1,0,1]
	v_lshlrev_b32_e32 v144, 16, v178
	v_and_b32_e32 v145, 0xffff0000, v178
	v_lshlrev_b32_e32 v146, 16, v179
	v_and_b32_e32 v147, 0xffff0000, v179
	v_pk_fma_f32 v[74:75], v[74:75], 0.5, v[144:145] op_sel_hi:[1,0,1]
	v_pk_fma_f32 v[76:77], v[76:77], 0.5, v[146:147] op_sel_hi:[1,0,1]
	v_cvt_pk_bf16_f32 v176, v78, v79
	v_cvt_pk_bf16_f32 v177, v80, v81
	v_cvt_pk_bf16_f32 v178, v74, v75
	v_cvt_pk_bf16_f32 v179, v76, v77
	global_store_dwordx4 v139, v[176:179], s[34:35] sc1
	v_pk_mul_f32 v[78:79], v[78:79], v[78:79]
	v_pk_fma_f32 v[78:79], v[80:81], v[80:81], v[78:79]
	v_pk_fma_f32 v[78:79], v[74:75], v[74:75], v[78:79]
	v_pk_fma_f32 v[78:79], v[76:77], v[76:77], v[78:79]
	s_waitcnt vmcnt(15)
	v_lshlrev_b32_e32 v144, 16, v180
	v_and_b32_e32 v145, 0xffff0000, v180
	v_lshlrev_b32_e32 v146, 16, v181
	v_and_b32_e32 v147, 0xffff0000, v181
	v_pk_fma_f32 v[70:71], v[70:71], 0.5, v[144:145] op_sel_hi:[1,0,1]
	v_pk_fma_f32 v[72:73], v[72:73], 0.5, v[146:147] op_sel_hi:[1,0,1]
	v_lshlrev_b32_e32 v144, 16, v182
	v_and_b32_e32 v145, 0xffff0000, v182
	v_lshlrev_b32_e32 v146, 16, v183
	v_and_b32_e32 v147, 0xffff0000, v183
	v_pk_fma_f32 v[66:67], v[66:67], 0.5, v[144:145] op_sel_hi:[1,0,1]
	v_pk_fma_f32 v[68:69], v[68:69], 0.5, v[146:147] op_sel_hi:[1,0,1]
	v_cvt_pk_bf16_f32 v180, v70, v71
	v_cvt_pk_bf16_f32 v181, v72, v73
	v_cvt_pk_bf16_f32 v182, v66, v67
	v_cvt_pk_bf16_f32 v183, v68, v69
	global_store_dwordx4 v139, v[180:183], s[34:35] offset:256 sc1
	v_pk_fma_f32 v[78:79], v[70:71], v[70:71], v[78:79]
	v_pk_fma_f32 v[78:79], v[72:73], v[72:73], v[78:79]
	v_pk_fma_f32 v[78:79], v[66:67], v[66:67], v[78:79]
	v_pk_fma_f32 v[78:79], v[68:69], v[68:69], v[78:79]
	v_add_f32_e32 v78, v78, v79
	v_add_u32_e32 v139, 0x40000, v138
	s_waitcnt vmcnt(15)
	v_lshlrev_b32_e32 v144, 16, v184
	v_and_b32_e32 v145, 0xffff0000, v184
	v_lshlrev_b32_e32 v146, 16, v185
	v_and_b32_e32 v147, 0xffff0000, v185
	v_pk_fma_f32 v[62:63], v[62:63], 0.5, v[144:145] op_sel_hi:[1,0,1]
	v_pk_fma_f32 v[64:65], v[64:65], 0.5, v[146:147] op_sel_hi:[1,0,1]
	v_lshlrev_b32_e32 v144, 16, v186
	v_and_b32_e32 v145, 0xffff0000, v186
	v_lshlrev_b32_e32 v146, 16, v187
	v_and_b32_e32 v147, 0xffff0000, v187
	v_pk_fma_f32 v[58:59], v[58:59], 0.5, v[144:145] op_sel_hi:[1,0,1]
	v_pk_fma_f32 v[60:61], v[60:61], 0.5, v[146:147] op_sel_hi:[1,0,1]
	v_cvt_pk_bf16_f32 v184, v62, v63
	v_cvt_pk_bf16_f32 v185, v64, v65
	v_cvt_pk_bf16_f32 v186, v58, v59
	v_cvt_pk_bf16_f32 v187, v60, v61
	global_store_dwordx4 v139, v[184:187], s[34:35] sc1
	v_pk_mul_f32 v[62:63], v[62:63], v[62:63]
	v_pk_fma_f32 v[62:63], v[64:65], v[64:65], v[62:63]
	v_pk_fma_f32 v[62:63], v[58:59], v[58:59], v[62:63]
	v_pk_fma_f32 v[62:63], v[60:61], v[60:61], v[62:63]
	s_waitcnt vmcnt(15)
	v_lshlrev_b32_e32 v144, 16, v188
	v_and_b32_e32 v145, 0xffff0000, v188
	v_lshlrev_b32_e32 v146, 16, v189
	v_and_b32_e32 v147, 0xffff0000, v189
	v_pk_fma_f32 v[54:55], v[54:55], 0.5, v[144:145] op_sel_hi:[1,0,1]
	v_pk_fma_f32 v[56:57], v[56:57], 0.5, v[146:147] op_sel_hi:[1,0,1]
	v_lshlrev_b32_e32 v144, 16, v190
	v_and_b32_e32 v145, 0xffff0000, v190
	v_lshlrev_b32_e32 v146, 16, v191
	v_and_b32_e32 v147, 0xffff0000, v191
	v_pk_fma_f32 v[50:51], v[50:51], 0.5, v[144:145] op_sel_hi:[1,0,1]
	v_pk_fma_f32 v[52:53], v[52:53], 0.5, v[146:147] op_sel_hi:[1,0,1]
	v_cvt_pk_bf16_f32 v188, v54, v55
	v_cvt_pk_bf16_f32 v189, v56, v57
	v_cvt_pk_bf16_f32 v190, v50, v51
	v_cvt_pk_bf16_f32 v191, v52, v53
	global_store_dwordx4 v139, v[188:191], s[34:35] offset:256 sc1
	v_pk_fma_f32 v[62:63], v[54:55], v[54:55], v[62:63]
	v_pk_fma_f32 v[62:63], v[56:57], v[56:57], v[62:63]
	v_pk_fma_f32 v[62:63], v[50:51], v[50:51], v[62:63]
	v_pk_fma_f32 v[62:63], v[52:53], v[52:53], v[62:63]
	v_add_f32_e32 v62, v62, v63
	v_add_u32_e32 v139, 0x48000, v138
	s_waitcnt vmcnt(15)
	v_lshlrev_b32_e32 v144, 16, v192
	v_and_b32_e32 v145, 0xffff0000, v192
	v_lshlrev_b32_e32 v146, 16, v193
	v_and_b32_e32 v147, 0xffff0000, v193
	v_pk_fma_f32 v[46:47], v[46:47], 0.5, v[144:145] op_sel_hi:[1,0,1]
	v_pk_fma_f32 v[48:49], v[48:49], 0.5, v[146:147] op_sel_hi:[1,0,1]
	v_lshlrev_b32_e32 v144, 16, v194
	v_and_b32_e32 v145, 0xffff0000, v194
	v_lshlrev_b32_e32 v146, 16, v195
	v_and_b32_e32 v147, 0xffff0000, v195
	v_pk_fma_f32 v[42:43], v[42:43], 0.5, v[144:145] op_sel_hi:[1,0,1]
	v_pk_fma_f32 v[44:45], v[44:45], 0.5, v[146:147] op_sel_hi:[1,0,1]
	v_cvt_pk_bf16_f32 v192, v46, v47
	v_cvt_pk_bf16_f32 v193, v48, v49
	v_cvt_pk_bf16_f32 v194, v42, v43
	v_cvt_pk_bf16_f32 v195, v44, v45
	global_store_dwordx4 v139, v[192:195], s[34:35] sc1
	v_pk_mul_f32 v[46:47], v[46:47], v[46:47]
	v_pk_fma_f32 v[46:47], v[48:49], v[48:49], v[46:47]
	v_pk_fma_f32 v[46:47], v[42:43], v[42:43], v[46:47]
	v_pk_fma_f32 v[46:47], v[44:45], v[44:45], v[46:47]
	s_waitcnt vmcnt(15)
; __device__ __forceinline__ float bflo(unsigned w) { return __uint_as_float(w << 16); }
; __device__ __forceinline__ float bfhi(unsigned w) { return __uint_as_float(w & 0xffff0000u); }
; __device__ __forceinline__ u32x4 pack8(const f32x4 a, const f32x4 b) { u32x4 w; w.x = cvt_pk_bf16(a[0], a[1]); w.y = cvt_pk_bf16(a[2], a[3]); w.z = cvt_pk_bf16(b[0], b[1]); w.w = cvt_pk_bf16(b[2], b[3]); return w; }
;     __device__ __forceinline__ void operator()(const f32x4 (&acc)[2][2][4][2], const Unit& u, int wr, int wc, int fr, int fq) const {
;         const int row0 = u.pm * 256 + wr * 64 + fr, col0 = u.pn * 256 + wc * 32 + 8 * fq;
; #pragma unroll
;         for (int ai = 0; ai < 2; ++ai)
; #pragma unroll
;             for (int m = 0; m < 4; ++m) {
;                 const int row = row0 + ai * 128 + m * 16; float p = 0.f;
; #pragma unroll
;                 for (int bj = 0; bj < 2; ++bj) {
;                     const size_t off = (size_t)row * D + col0 + bj * 128;
;                     const u32x4 xx = *(const u32x4*)(xb + off);
;                     const f32x4 x0 = (f32x4){bflo(xx.x), bfhi(xx.x), bflo(xx.y), bfhi(xx.y)}, x1 = (f32x4){bflo(xx.z), bfhi(xx.z), bflo(xx.w), bfhi(xx.w)};
;                     const f32x4 y0 = x0 + acc[ai][bj][m][0] * scale, y1 = x1 + acc[ai][bj][m][1] * scale;
;                     *(u32x4*)(xb + off) = pack8(y0, y1);
;                     const f32x4 q = y0 * y0 + y1 * y1; p += (q[0] + q[1]) + (q[2] + q[3]);
;                 }
;                 p += __shfl_xor(p, 16); p += __shfl_xor(p, 32);
;                 if (fq == 0) ssn[(size_t)row * 16 + u.pn * 4 + wc] = p;
;             }
	v_lshlrev_b32_e32 v144, 16, v196
	v_and_b32_e32 v145, 0xffff0000, v196
	v_lshlrev_b32_e32 v146, 16, v197
	v_and_b32_e32 v147, 0xffff0000, v197
	v_pk_fma_f32 v[38:39], v[38:39], 0.5, v[144:145] op_sel_hi:[1,0,1]
	v_pk_fma_f32 v[40:41], v[40:41], 0.5, v[146:147] op_sel_hi:[1,0,1]
	v_lshlrev_b32_e32 v144, 16, v198
	v_and_b32_e32 v145, 0xffff0000, v198
	v_lshlrev_b32_e32 v146, 16, v199
	v_and_b32_e32 v147, 0xffff0000, v199
	v_pk_fma_f32 v[34:35], v[34:35], 0.5, v[144:145] op_sel_hi:[1,0,1]
	v_pk_fma_f32 v[36:37], v[36:37], 0.5, v[146:147] op_sel_hi:[1,0,1]
	v_cvt_pk_bf16_f32 v196, v38, v39
	v_cvt_pk_bf16_f32 v197, v40, v41
	v_cvt_pk_bf16_f32 v198, v34, v35
	v_cvt_pk_bf16_f32 v199, v36, v37
	global_store_dwordx4 v139, v[196:199], s[34:35] offset:256 sc1
	v_pk_fma_f32 v[46:47], v[38:39], v[38:39], v[46:47]
	v_pk_fma_f32 v[46:47], v[40:41], v[40:41], v[46:47]
	v_pk_fma_f32 v[46:47], v[34:35], v[34:35], v[46:47]
	v_pk_fma_f32 v[46:47], v[36:37], v[36:37], v[46:47]
	v_add_f32_e32 v46, v46, v47
	v_add_u32_e32 v139, 0x50000, v138
	s_waitcnt vmcnt(15)
	v_lshlrev_b32_e32 v144, 16, v200
	v_and_b32_e32 v145, 0xffff0000, v200
	v_lshlrev_b32_e32 v146, 16, v201
	v_and_b32_e32 v147, 0xffff0000, v201
	v_pk_fma_f32 v[30:31], v[30:31], 0.5, v[144:145] op_sel_hi:[1,0,1]
	v_pk_fma_f32 v[32:33], v[32:33], 0.5, v[146:147] op_sel_hi:[1,0,1]
	v_lshlrev_b32_e32 v144, 16, v202
	v_and_b32_e32 v145, 0xffff0000, v202
	v_lshlrev_b32_e32 v146, 16, v203
	v_and_b32_e32 v147, 0xffff0000, v203
	v_pk_fma_f32 v[26:27], v[26:27], 0.5, v[144:145] op_sel_hi:[1,0,1]
	v_pk_fma_f32 v[28:29], v[28:29], 0.5, v[146:147] op_sel_hi:[1,0,1]
	v_cvt_pk_bf16_f32 v200, v30, v31
	v_cvt_pk_bf16_f32 v201, v32, v33
	v_cvt_pk_bf16_f32 v202, v26, v27
	v_cvt_pk_bf16_f32 v203, v28, v29
	global_store_dwordx4 v139, v[200:203], s[34:35] sc1
	v_pk_mul_f32 v[30:31], v[30:31], v[30:31]
	v_pk_fma_f32 v[30:31], v[32:33], v[32:33], v[30:31]
	v_pk_fma_f32 v[30:31], v[26:27], v[26:27], v[30:31]
	v_pk_fma_f32 v[30:31], v[28:29], v[28:29], v[30:31]
	s_waitcnt vmcnt(15)
	v_lshlrev_b32_e32 v144, 16, v224
	v_and_b32_e32 v145, 0xffff0000, v224
	v_lshlrev_b32_e32 v146, 16, v225
	v_and_b32_e32 v147, 0xffff0000, v225
	v_pk_fma_f32 v[22:23], v[22:23], 0.5, v[144:145] op_sel_hi:[1,0,1]
	v_pk_fma_f32 v[24:25], v[24:25], 0.5, v[146:147] op_sel_hi:[1,0,1]
	v_lshlrev_b32_e32 v144, 16, v226
	v_and_b32_e32 v145, 0xffff0000, v226
	v_lshlrev_b32_e32 v146, 16, v227
	v_and_b32_e32 v147, 0xffff0000, v227
	v_pk_fma_f32 v[18:19], v[18:19], 0.5, v[144:145] op_sel_hi:[1,0,1]
	v_pk_fma_f32 v[20:21], v[20:21], 0.5, v[146:147] op_sel_hi:[1,0,1]
	v_cvt_pk_bf16_f32 v224, v22, v23
	v_cvt_pk_bf16_f32 v225, v24, v25
	v_cvt_pk_bf16_f32 v226, v18, v19
	v_cvt_pk_bf16_f32 v227, v20, v21
	global_store_dwordx4 v139, v[224:227], s[34:35] offset:256 sc1
	v_pk_fma_f32 v[30:31], v[22:23], v[22:23], v[30:31]
	v_pk_fma_f32 v[30:31], v[24:25], v[24:25], v[30:31]
	v_pk_fma_f32 v[30:31], v[18:19], v[18:19], v[30:31]
	v_pk_fma_f32 v[30:31], v[20:21], v[20:21], v[30:31]
	v_add_f32_e32 v30, v30, v31
	v_add_u32_e32 v139, 0x58000, v138
	s_waitcnt vmcnt(15)
	v_lshlrev_b32_e32 v144, 16, v228
	v_and_b32_e32 v145, 0xffff0000, v228
	v_lshlrev_b32_e32 v146, 16, v229
	v_and_b32_e32 v147, 0xffff0000, v229
	v_pk_fma_f32 v[14:15], v[14:15], 0.5, v[144:145] op_sel_hi:[1,0,1]
	v_pk_fma_f32 v[16:17], v[16:17], 0.5, v[146:147] op_sel_hi:[1,0,1]
	v_lshlrev_b32_e32 v144, 16, v230
	v_and_b32_e32 v145, 0xffff0000, v230
	v_lshlrev_b32_e32 v146, 16, v231
	v_and_b32_e32 v147, 0xffff0000, v231
	v_pk_fma_f32 v[10:11], v[10:11], 0.5, v[144:145] op_sel_hi:[1,0,1]
	v_pk_fma_f32 v[12:13], v[12:13], 0.5, v[146:147] op_sel_hi:[1,0,1]
	v_cvt_pk_bf16_f32 v228, v14, v15
	v_cvt_pk_bf16_f32 v229, v16, v17
	v_cvt_pk_bf16_f32 v230, v10, v11
	v_cvt_pk_bf16_f32 v231, v12, v13
	global_store_dwordx4 v139, v[228:231], s[34:35] sc1
	v_pk_mul_f32 v[14:15], v[14:15], v[14:15]
	v_pk_fma_f32 v[14:15], v[16:17], v[16:17], v[14:15]
	v_pk_fma_f32 v[14:15], v[10:11], v[10:11], v[14:15]
	v_pk_fma_f32 v[14:15], v[12:13], v[12:13], v[14:15]
	s_waitcnt vmcnt(15)
	v_lshlrev_b32_e32 v144, 16, v232
	v_and_b32_e32 v145, 0xffff0000, v232
	v_lshlrev_b32_e32 v146, 16, v233
	v_and_b32_e32 v147, 0xffff0000, v233
	v_pk_fma_f32 v[6:7], v[6:7], 0.5, v[144:145] op_sel_hi:[1,0,1]
	v_pk_fma_f32 v[8:9], v[8:9], 0.5, v[146:147] op_sel_hi:[1,0,1]
	v_lshlrev_b32_e32 v144, 16, v234
	v_and_b32_e32 v145, 0xffff0000, v234
	v_lshlrev_b32_e32 v146, 16, v235
	v_and_b32_e32 v147, 0xffff0000, v235
	v_pk_fma_f32 v[2:3], v[2:3], 0.5, v[144:145] op_sel_hi:[1,0,1]
	v_pk_fma_f32 v[4:5], v[4:5], 0.5, v[146:147] op_sel_hi:[1,0,1]
	v_cvt_pk_bf16_f32 v232, v6, v7
	v_cvt_pk_bf16_f32 v233, v8, v9
	v_cvt_pk_bf16_f32 v234, v2, v3
	v_cvt_pk_bf16_f32 v235, v4, v5
	global_store_dwordx4 v139, v[232:235], s[34:35] offset:256 sc1
	v_pk_fma_f32 v[14:15], v[6:7], v[6:7], v[14:15]
	v_pk_fma_f32 v[14:15], v[8:9], v[8:9], v[14:15]
	v_pk_fma_f32 v[14:15], v[2:3], v[2:3], v[14:15]
	v_pk_fma_f32 v[14:15], v[4:5], v[4:5], v[14:15]
	v_add_f32_e32 v14, v14, v15
	v_xor_b32_e32 v140, 16, v213
	v_xor_b32_e32 v141, 32, v213
	v_lshlrev_b32_e32 v140, 2, v140
	v_lshlrev_b32_e32 v141, 2, v141
	ds_bpermute_b32 v127, v140, v126
	ds_bpermute_b32 v111, v140, v110
	ds_bpermute_b32 v95, v140, v94
	ds_bpermute_b32 v79, v140, v78
	ds_bpermute_b32 v63, v140, v62
	ds_bpermute_b32 v47, v140, v46
	ds_bpermute_b32 v31, v140, v30
	ds_bpermute_b32 v15, v140, v14
	s_waitcnt lgkmcnt(0)
	v_add_f32_e32 v126, v126, v127
	v_add_f32_e32 v110, v110, v111
	v_add_f32_e32 v94, v94, v95
	v_add_f32_e32 v78, v78, v79
	v_add_f32_e32 v62, v62, v63
	v_add_f32_e32 v46, v46, v47
	v_add_f32_e32 v30, v30, v31
	v_add_f32_e32 v14, v14, v15
	ds_bpermute_b32 v127, v141, v126
	ds_bpermute_b32 v111, v141, v110
	ds_bpermute_b32 v95, v141, v94
	ds_bpermute_b32 v79, v141, v78
	ds_bpermute_b32 v63, v141, v62
	ds_bpermute_b32 v47, v141, v46
	ds_bpermute_b32 v31, v141, v30
	ds_bpermute_b32 v15, v141, v14
	s_waitcnt lgkmcnt(0)
	v_add_f32_e32 v126, v126, v127
	v_add_f32_e32 v110, v110, v111
	v_add_f32_e32 v94, v94, v95
	v_add_f32_e32 v78, v78, v79
	v_add_f32_e32 v62, v62, v63
	v_add_f32_e32 v46, v46, v47
	v_add_f32_e32 v30, v30, v31
	v_add_f32_e32 v14, v14, v15
	v_lshl_add_u32 v204, s46, 8, v148
	s_lshl_b32 s14, s45, 4
	s_lshl_b32 s15, s31, 2
	s_add_i32 s14, s14, s15
	v_lshlrev_b32_e32 v204, 6, v204
	v_add_u32_e32 v204, s14, v204
	v_add_u32_e32 v205, 0x2000, v204
	s_and_saveexec_b64 s[16:17], s[2:3]
	global_store_dword v204, v126, s[0:1] sc1
	global_store_dword v204, v110, s[0:1] offset:1024 sc1
	global_store_dword v204, v94, s[0:1] offset:2048 sc1
	global_store_dword v204, v78, s[0:1] offset:3072 sc1
	global_store_dword v205, v62, s[0:1] sc1
	global_store_dword v205, v46, s[0:1] offset:1024 sc1
	global_store_dword v205, v30, s[0:1] offset:2048 sc1
	global_store_dword v205, v14, s[0:1] offset:3072 sc1
	s_or_b64 exec, exec, s[16:17]
	s_and_b64 vcc, exec, s[4:5]
	s_mov_b64 s[4:5], -1
	s_cbranch_vccnz .LBB0_350
	s_andn2_b64 vcc, exec, s[8:9]
	s_cbranch_vccnz .LBB0_349
	s_barrier
	s_branch .LBB0_349

; __device__ __forceinline__ float bflo(unsigned w) { return __uint_as_float(w << 16); }
; __device__ __forceinline__ float bfhi(unsigned w) { return __uint_as_float(w & 0xffff0000u); }
; __device__ __forceinline__ u32x4 pack8(const f32x4 a, const f32x4 b) { u32x4 w; w.x = cvt_pk_bf16(a[0], a[1]); w.y = cvt_pk_bf16(a[2], a[3]); w.z = cvt_pk_bf16(b[0], b[1]); w.w = cvt_pk_bf16(b[2], b[3]); return w; }
;     __device__ __forceinline__ void operator()(const f32x4 (&acc)[2][2][4][2], const Unit& u, int wr, int wc, int fr, int fq) const {
;         const int row0 = u.pm * 256 + wr * 64 + fr, col0 = u.pn * 256 + wc * 32 + 8 * fq;
; #pragma unroll
;         for (int ai = 0; ai < 2; ++ai)
; #pragma unroll
;             for (int m = 0; m < 4; ++m) {
;                 const int row = row0 + ai * 128 + m * 16;
; #pragma unroll
;                 for (int bj = 0; bj < 2; ++bj) {
;                     const int c = col0 + bj * 128;
;                     const u32x4 g = *(const u32x4*)(G + (size_t)row * P2W + c);
;                     f32x4 o0 = acc[ai][bj][m][0], o1 = acc[ai][bj][m][1];
;                     o0[0] *= bflo(g.x); o0[1] *= bfhi(g.x); o0[2] *= bflo(g.y); o0[3] *= bfhi(g.y); o1[0] *= bflo(g.z); o1[1] *= bfhi(g.z); o1[2] *= bflo(g.w); o1[3] *= bfhi(g.w);
;                     *(u32x4*)(T + (size_t)row * D + c) = pack8(o0, o1);
;                 }
;             }
.LBB0_894:
	s_waitcnt vmcnt(15)
	v_lshlrev_b32_e32 v148, 16, v144
	v_and_b32_e32 v149, 0xffff0000, v144
	v_pk_mul_f32 v[126:127], v[126:127], v[148:149]
	v_lshlrev_b32_e32 v154, 16, v145
	v_and_b32_e32 v155, 0xffff0000, v145
	v_pk_mul_f32 v[128:129], v[128:129], v[154:155]
	v_lshlrev_b32_e32 v148, 16, v146
	v_and_b32_e32 v149, 0xffff0000, v146
	v_pk_mul_f32 v[122:123], v[122:123], v[148:149]
	v_lshlrev_b32_e32 v154, 16, v147
	v_and_b32_e32 v155, 0xffff0000, v147
	v_pk_mul_f32 v[124:125], v[124:125], v[154:155]
	v_cvt_pk_bf16_f32 v144, v126, v127
	v_cvt_pk_bf16_f32 v145, v128, v129
	v_cvt_pk_bf16_f32 v146, v122, v123
	v_cvt_pk_bf16_f32 v147, v124, v125
	global_store_dwordx4 v139, v[144:147], s[36:37] sc1
	s_waitcnt vmcnt(15)
	v_lshlrev_b32_e32 v148, 16, v156
	v_and_b32_e32 v149, 0xffff0000, v156
	v_pk_mul_f32 v[118:119], v[118:119], v[148:149]
	v_lshlrev_b32_e32 v154, 16, v157
	v_and_b32_e32 v155, 0xffff0000, v157
	v_pk_mul_f32 v[120:121], v[120:121], v[154:155]
	v_lshlrev_b32_e32 v148, 16, v158
	v_and_b32_e32 v149, 0xffff0000, v158
	v_pk_mul_f32 v[114:115], v[114:115], v[148:149]
	v_lshlrev_b32_e32 v154, 16, v159
	v_and_b32_e32 v155, 0xffff0000, v159
	v_pk_mul_f32 v[116:117], v[116:117], v[154:155]
	v_cvt_pk_bf16_f32 v156, v118, v119
	v_cvt_pk_bf16_f32 v157, v120, v121
	v_cvt_pk_bf16_f32 v158, v114, v115
	v_cvt_pk_bf16_f32 v159, v116, v117
	global_store_dwordx4 v139, v[156:159], s[36:37] offset:256 sc1
	v_add_u32_e32 v141, 0x8000, v139
	s_waitcnt vmcnt(15)
	v_lshlrev_b32_e32 v148, 16, v160
	v_and_b32_e32 v149, 0xffff0000, v160
	v_pk_mul_f32 v[110:111], v[110:111], v[148:149]
	v_lshlrev_b32_e32 v154, 16, v161
	v_and_b32_e32 v155, 0xffff0000, v161
	v_pk_mul_f32 v[112:113], v[112:113], v[154:155]
	v_lshlrev_b32_e32 v148, 16, v162
	v_and_b32_e32 v149, 0xffff0000, v162
	v_pk_mul_f32 v[106:107], v[106:107], v[148:149]
	v_lshlrev_b32_e32 v154, 16, v163
	v_and_b32_e32 v155, 0xffff0000, v163
	v_pk_mul_f32 v[108:109], v[108:109], v[154:155]
	v_cvt_pk_bf16_f32 v160, v110, v111
	v_cvt_pk_bf16_f32 v161, v112, v113
	v_cvt_pk_bf16_f32 v162, v106, v107
	v_cvt_pk_bf16_f32 v163, v108, v109
	global_store_dwordx4 v141, v[160:163], s[36:37] sc1
	s_waitcnt vmcnt(15)
	v_lshlrev_b32_e32 v148, 16, v164
	v_and_b32_e32 v149, 0xffff0000, v164
	v_pk_mul_f32 v[102:103], v[102:103], v[148:149]
	v_lshlrev_b32_e32 v154, 16, v165
	v_and_b32_e32 v155, 0xffff0000, v165
	v_pk_mul_f32 v[104:105], v[104:105], v[154:155]
	v_lshlrev_b32_e32 v148, 16, v166
	v_and_b32_e32 v149, 0xffff0000, v166
	v_pk_mul_f32 v[98:99], v[98:99], v[148:149]
	v_lshlrev_b32_e32 v154, 16, v167
	v_and_b32_e32 v155, 0xffff0000, v167
	v_pk_mul_f32 v[100:101], v[100:101], v[154:155]
	v_cvt_pk_bf16_f32 v164, v102, v103
	v_cvt_pk_bf16_f32 v165, v104, v105
	v_cvt_pk_bf16_f32 v166, v98, v99
	v_cvt_pk_bf16_f32 v167, v100, v101
	global_store_dwordx4 v141, v[164:167], s[36:37] offset:256 sc1
	v_add_u32_e32 v141, 0x10000, v139
	s_waitcnt vmcnt(15)
	v_lshlrev_b32_e32 v148, 16, v168
	v_and_b32_e32 v149, 0xffff0000, v168
	v_pk_mul_f32 v[94:95], v[94:95], v[148:149]
	v_lshlrev_b32_e32 v154, 16, v169
	v_and_b32_e32 v155, 0xffff0000, v169
	v_pk_mul_f32 v[96:97], v[96:97], v[154:155]
	v_lshlrev_b32_e32 v148, 16, v170
	v_and_b32_e32 v149, 0xffff0000, v170
	v_pk_mul_f32 v[90:91], v[90:91], v[148:149]
	v_lshlrev_b32_e32 v154, 16, v171
	v_and_b32_e32 v155, 0xffff0000, v171
	v_pk_mul_f32 v[92:93], v[92:93], v[154:155]
	v_cvt_pk_bf16_f32 v168, v94, v95
	v_cvt_pk_bf16_f32 v169, v96, v97
	v_cvt_pk_bf16_f32 v170, v90, v91
	v_cvt_pk_bf16_f32 v171, v92, v93
	global_store_dwordx4 v141, v[168:171], s[36:37] sc1
	s_waitcnt vmcnt(15)
	v_lshlrev_b32_e32 v148, 16, v172
	v_and_b32_e32 v149, 0xffff0000, v172
	v_pk_mul_f32 v[86:87], v[86:87], v[148:149]
	v_lshlrev_b32_e32 v154, 16, v173
	v_and_b32_e32 v155, 0xffff0000, v173
	v_pk_mul_f32 v[88:89], v[88:89], v[154:155]
	v_lshlrev_b32_e32 v148, 16, v174
	v_and_b32_e32 v149, 0xffff0000, v174
	v_pk_mul_f32 v[82:83], v[82:83], v[148:149]
	v_lshlrev_b32_e32 v154, 16, v175
	v_and_b32_e32 v155, 0xffff0000, v175
	v_pk_mul_f32 v[84:85], v[84:85], v[154:155]
	v_cvt_pk_bf16_f32 v172, v86, v87
	v_cvt_pk_bf16_f32 v173, v88, v89
	v_cvt_pk_bf16_f32 v174, v82, v83
	v_cvt_pk_bf16_f32 v175, v84, v85
	global_store_dwordx4 v141, v[172:175], s[36:37] offset:256 sc1
	v_add_u32_e32 v141, 0x18000, v139
	s_waitcnt vmcnt(15)
	v_lshlrev_b32_e32 v148, 16, v176
	v_and_b32_e32 v149, 0xffff0000, v176
	v_pk_mul_f32 v[78:79], v[78:79], v[148:149]
	v_lshlrev_b32_e32 v154, 16, v177
	v_and_b32_e32 v155, 0xffff0000, v177
	v_pk_mul_f32 v[80:81], v[80:81], v[154:155]
	v_lshlrev_b32_e32 v148, 16, v178
	v_and_b32_e32 v149, 0xffff0000, v178
	v_pk_mul_f32 v[74:75], v[74:75], v[148:149]
	v_lshlrev_b32_e32 v154, 16, v179
	v_and_b32_e32 v155, 0xffff0000, v179
	v_pk_mul_f32 v[76:77], v[76:77], v[154:155]
	v_cvt_pk_bf16_f32 v176, v78, v79
	v_cvt_pk_bf16_f32 v177, v80, v81
	v_cvt_pk_bf16_f32 v178, v74, v75
	v_cvt_pk_bf16_f32 v179, v76, v77
	global_store_dwordx4 v141, v[176:179], s[36:37] sc1
	s_waitcnt vmcnt(15)
	v_lshlrev_b32_e32 v148, 16, v180
	v_and_b32_e32 v149, 0xffff0000, v180
	v_pk_mul_f32 v[70:71], v[70:71], v[148:149]
	v_lshlrev_b32_e32 v154, 16, v181
	v_and_b32_e32 v155, 0xffff0000, v181
	v_pk_mul_f32 v[72:73], v[72:73], v[154:155]
	v_lshlrev_b32_e32 v148, 16, v182
	v_and_b32_e32 v149, 0xffff0000, v182
	v_pk_mul_f32 v[66:67], v[66:67], v[148:149]
	v_lshlrev_b32_e32 v154, 16, v183
	v_and_b32_e32 v155, 0xffff0000, v183
	v_pk_mul_f32 v[68:69], v[68:69], v[154:155]
	v_cvt_pk_bf16_f32 v180, v70, v71
	v_cvt_pk_bf16_f32 v181, v72, v73
	v_cvt_pk_bf16_f32 v182, v66, v67
	v_cvt_pk_bf16_f32 v183, v68, v69
	global_store_dwordx4 v141, v[180:183], s[36:37] offset:256 sc1
	v_add_u32_e32 v141, 0x40000, v139
	s_waitcnt vmcnt(15)
; __device__ __forceinline__ float bflo(unsigned w) { return __uint_as_float(w << 16); }
; __device__ __forceinline__ float bfhi(unsigned w) { return __uint_as_float(w & 0xffff0000u); }
; __device__ __forceinline__ u32x4 pack8(const f32x4 a, const f32x4 b) { u32x4 w; w.x = cvt_pk_bf16(a[0], a[1]); w.y = cvt_pk_bf16(a[2], a[3]); w.z = cvt_pk_bf16(b[0], b[1]); w.w = cvt_pk_bf16(b[2], b[3]); return w; }
;     __device__ __forceinline__ void operator()(const f32x4 (&acc)[2][2][4][2], const Unit& u, int wr, int wc, int fr, int fq) const {
;         const int row0 = u.pm * 256 + wr * 64 + fr, col0 = u.pn * 256 + wc * 32 + 8 * fq;
; #pragma unroll
;         for (int ai = 0; ai < 2; ++ai)
; #pragma unroll
;             for (int m = 0; m < 4; ++m) {
;                 const int row = row0 + ai * 128 + m * 16;
; #pragma unroll
;                 for (int bj = 0; bj < 2; ++bj) {
;                     const int c = col0 + bj * 128;
;                     const u32x4 g = *(const u32x4*)(G + (size_t)row * P2W + c);
;                     f32x4 o0 = acc[ai][bj][m][0], o1 = acc[ai][bj][m][1];
;                     o0[0] *= bflo(g.x); o0[1] *= bfhi(g.x); o0[2] *= bflo(g.y); o0[3] *= bfhi(g.y); o1[0] *= bflo(g.z); o1[1] *= bfhi(g.z); o1[2] *= bflo(g.w); o1[3] *= bfhi(g.w);
;                     *(u32x4*)(T + (size_t)row * D + c) = pack8(o0, o1);
;                 }
;             }
	v_lshlrev_b32_e32 v148, 16, v184
	v_and_b32_e32 v149, 0xffff0000, v184
	v_pk_mul_f32 v[62:63], v[62:63], v[148:149]
	v_lshlrev_b32_e32 v154, 16, v185
	v_and_b32_e32 v155, 0xffff0000, v185
	v_pk_mul_f32 v[64:65], v[64:65], v[154:155]
	v_lshlrev_b32_e32 v148, 16, v186
	v_and_b32_e32 v149, 0xffff0000, v186
	v_pk_mul_f32 v[58:59], v[58:59], v[148:149]
	v_lshlrev_b32_e32 v154, 16, v187
	v_and_b32_e32 v155, 0xffff0000, v187
	v_pk_mul_f32 v[60:61], v[60:61], v[154:155]
	v_cvt_pk_bf16_f32 v184, v62, v63
	v_cvt_pk_bf16_f32 v185, v64, v65
	v_cvt_pk_bf16_f32 v186, v58, v59
	v_cvt_pk_bf16_f32 v187, v60, v61
	global_store_dwordx4 v141, v[184:187], s[36:37] sc1
	s_waitcnt vmcnt(15)
	v_lshlrev_b32_e32 v148, 16, v188
	v_and_b32_e32 v149, 0xffff0000, v188
	v_pk_mul_f32 v[54:55], v[54:55], v[148:149]
	v_lshlrev_b32_e32 v154, 16, v189
	v_and_b32_e32 v155, 0xffff0000, v189
	v_pk_mul_f32 v[56:57], v[56:57], v[154:155]
	v_lshlrev_b32_e32 v148, 16, v190
	v_and_b32_e32 v149, 0xffff0000, v190
	v_pk_mul_f32 v[50:51], v[50:51], v[148:149]
	v_lshlrev_b32_e32 v154, 16, v191
	v_and_b32_e32 v155, 0xffff0000, v191
	v_pk_mul_f32 v[52:53], v[52:53], v[154:155]
	v_cvt_pk_bf16_f32 v188, v54, v55
	v_cvt_pk_bf16_f32 v189, v56, v57
	v_cvt_pk_bf16_f32 v190, v50, v51
	v_cvt_pk_bf16_f32 v191, v52, v53
	global_store_dwordx4 v141, v[188:191], s[36:37] offset:256 sc1
	v_add_u32_e32 v141, 0x48000, v139
	s_waitcnt vmcnt(15)
	v_lshlrev_b32_e32 v148, 16, v192
	v_and_b32_e32 v149, 0xffff0000, v192
	v_pk_mul_f32 v[46:47], v[46:47], v[148:149]
	v_lshlrev_b32_e32 v154, 16, v193
	v_and_b32_e32 v155, 0xffff0000, v193
	v_pk_mul_f32 v[48:49], v[48:49], v[154:155]
	v_lshlrev_b32_e32 v148, 16, v194
	v_and_b32_e32 v149, 0xffff0000, v194
	v_pk_mul_f32 v[42:43], v[42:43], v[148:149]
	v_lshlrev_b32_e32 v154, 16, v195
	v_and_b32_e32 v155, 0xffff0000, v195
	v_pk_mul_f32 v[44:45], v[44:45], v[154:155]
	v_cvt_pk_bf16_f32 v192, v46, v47
	v_cvt_pk_bf16_f32 v193, v48, v49
	v_cvt_pk_bf16_f32 v194, v42, v43
	v_cvt_pk_bf16_f32 v195, v44, v45
	global_store_dwordx4 v141, v[192:195], s[36:37] sc1
	s_waitcnt vmcnt(15)
	v_lshlrev_b32_e32 v148, 16, v196
	v_and_b32_e32 v149, 0xffff0000, v196
	v_pk_mul_f32 v[38:39], v[38:39], v[148:149]
	v_lshlrev_b32_e32 v154, 16, v197
	v_and_b32_e32 v155, 0xffff0000, v197
	v_pk_mul_f32 v[40:41], v[40:41], v[154:155]
	v_lshlrev_b32_e32 v148, 16, v198
	v_and_b32_e32 v149, 0xffff0000, v198
	v_pk_mul_f32 v[34:35], v[34:35], v[148:149]
	v_lshlrev_b32_e32 v154, 16, v199
	v_and_b32_e32 v155, 0xffff0000, v199
	v_pk_mul_f32 v[36:37], v[36:37], v[154:155]
	v_cvt_pk_bf16_f32 v196, v38, v39
	v_cvt_pk_bf16_f32 v197, v40, v41
	v_cvt_pk_bf16_f32 v198, v34, v35
	v_cvt_pk_bf16_f32 v199, v36, v37
	global_store_dwordx4 v141, v[196:199], s[36:37] offset:256 sc1
	v_add_u32_e32 v141, 0x50000, v139
	s_waitcnt vmcnt(15)
	v_lshlrev_b32_e32 v148, 16, v200
	v_and_b32_e32 v149, 0xffff0000, v200
	v_pk_mul_f32 v[30:31], v[30:31], v[148:149]
	v_lshlrev_b32_e32 v154, 16, v201
	v_and_b32_e32 v155, 0xffff0000, v201
	v_pk_mul_f32 v[32:33], v[32:33], v[154:155]
	v_lshlrev_b32_e32 v148, 16, v202
	v_and_b32_e32 v149, 0xffff0000, v202
	v_pk_mul_f32 v[26:27], v[26:27], v[148:149]
	v_lshlrev_b32_e32 v154, 16, v203
	v_and_b32_e32 v155, 0xffff0000, v203
	v_pk_mul_f32 v[28:29], v[28:29], v[154:155]
	v_cvt_pk_bf16_f32 v200, v30, v31
	v_cvt_pk_bf16_f32 v201, v32, v33
	v_cvt_pk_bf16_f32 v202, v26, v27
	v_cvt_pk_bf16_f32 v203, v28, v29
	global_store_dwordx4 v141, v[200:203], s[36:37] sc1
	s_waitcnt vmcnt(15)
	v_lshlrev_b32_e32 v148, 16, v224
	v_and_b32_e32 v149, 0xffff0000, v224
	v_pk_mul_f32 v[22:23], v[22:23], v[148:149]
	v_lshlrev_b32_e32 v154, 16, v225
	v_and_b32_e32 v155, 0xffff0000, v225
	v_pk_mul_f32 v[24:25], v[24:25], v[154:155]
	v_lshlrev_b32_e32 v148, 16, v226
	v_and_b32_e32 v149, 0xffff0000, v226
	v_pk_mul_f32 v[18:19], v[18:19], v[148:149]
	v_lshlrev_b32_e32 v154, 16, v227
	v_and_b32_e32 v155, 0xffff0000, v227
	v_pk_mul_f32 v[20:21], v[20:21], v[154:155]
	v_cvt_pk_bf16_f32 v224, v22, v23
	v_cvt_pk_bf16_f32 v225, v24, v25
	v_cvt_pk_bf16_f32 v226, v18, v19
	v_cvt_pk_bf16_f32 v227, v20, v21
	global_store_dwordx4 v141, v[224:227], s[36:37] offset:256 sc1
	v_add_u32_e32 v141, 0x58000, v139
	s_waitcnt vmcnt(15)
	v_lshlrev_b32_e32 v148, 16, v228
	v_and_b32_e32 v149, 0xffff0000, v228
	v_pk_mul_f32 v[14:15], v[14:15], v[148:149]
	v_lshlrev_b32_e32 v154, 16, v229
	v_and_b32_e32 v155, 0xffff0000, v229
	v_pk_mul_f32 v[16:17], v[16:17], v[154:155]
	v_lshlrev_b32_e32 v148, 16, v230
	v_and_b32_e32 v149, 0xffff0000, v230
	v_pk_mul_f32 v[10:11], v[10:11], v[148:149]
	v_lshlrev_b32_e32 v154, 16, v231
	v_and_b32_e32 v155, 0xffff0000, v231
	v_pk_mul_f32 v[12:13], v[12:13], v[154:155]
	v_cvt_pk_bf16_f32 v228, v14, v15
	v_cvt_pk_bf16_f32 v229, v16, v17
	v_cvt_pk_bf16_f32 v230, v10, v11
	v_cvt_pk_bf16_f32 v231, v12, v13
	global_store_dwordx4 v141, v[228:231], s[36:37] sc1
	s_waitcnt vmcnt(15)
	v_lshlrev_b32_e32 v148, 16, v232
	v_and_b32_e32 v149, 0xffff0000, v232
	v_pk_mul_f32 v[6:7], v[6:7], v[148:149]
	v_lshlrev_b32_e32 v154, 16, v233
	v_and_b32_e32 v155, 0xffff0000, v233
	v_pk_mul_f32 v[8:9], v[8:9], v[154:155]
	v_lshlrev_b32_e32 v148, 16, v234
	v_and_b32_e32 v149, 0xffff0000, v234
	v_pk_mul_f32 v[2:3], v[2:3], v[148:149]
	v_lshlrev_b32_e32 v154, 16, v235
	v_and_b32_e32 v155, 0xffff0000, v235
	v_pk_mul_f32 v[4:5], v[4:5], v[154:155]
	v_cvt_pk_bf16_f32 v232, v6, v7
	v_cvt_pk_bf16_f32 v233, v8, v9
	v_cvt_pk_bf16_f32 v234, v2, v3
	v_cvt_pk_bf16_f32 v235, v4, v5
	global_store_dwordx4 v141, v[232:235], s[36:37] offset:256 sc1
	s_mov_b64 s[14:15], -1
	s_andn2_b64 vcc, exec, s[2:3]
	s_cbranch_vccnz .LBB0_883
	s_andn2_b64 vcc, exec, s[0:1]
	s_cbranch_vccnz .LBB0_882
	s_barrier
	s_branch .LBB0_882

; __device__ __forceinline__ float bflo(unsigned w) { return __uint_as_float(w << 16); }
; __device__ __forceinline__ float bfhi(unsigned w) { return __uint_as_float(w & 0xffff0000u); }
; __device__ __forceinline__ u32x4 pack8(const f32x4 a, const f32x4 b) { u32x4 w; w.x = cvt_pk_bf16(a[0], a[1]); w.y = cvt_pk_bf16(a[2], a[3]); w.z = cvt_pk_bf16(b[0], b[1]); w.w = cvt_pk_bf16(b[2], b[3]); return w; }
;     __device__ __forceinline__ void operator()(const f32x4 (&acc)[2][2][4][2], const Unit& u, int wr, int wc, int fr, int fq) const {
;         const int row0 = u.pm * 256 + wr * 64 + fr, col0 = u.pn * 256 + wc * 32 + 8 * fq;
; #pragma unroll
;         for (int ai = 0; ai < 2; ++ai)
; #pragma unroll
;             for (int m = 0; m < 4; ++m) {
;                 const int row = row0 + ai * 128 + m * 16;
; #pragma unroll
;                 for (int bj = 0; bj < 2; ++bj) {
;                     const int c = col0 + bj * 128;
;                     const u32x4 g = *(const u32x4*)(G + (size_t)row * P2W + c);
;                     const u32x4 t = *(const u32x4*)(T + (size_t)row * D + c);
;                     f32x4 o0 = acc[ai][bj][m][0], o1 = acc[ai][bj][m][1];
;                     o0[0] = o0[0] * bflo(g.x) + bflo(t.x); o0[1] = o0[1] * bfhi(g.x) + bfhi(t.x); o0[2] = o0[2] * bflo(g.y) + bflo(t.y); o0[3] = o0[3] * bfhi(g.y) + bfhi(t.y);
;                     o1[0] = o1[0] * bflo(g.z) + bflo(t.z); o1[1] = o1[1] * bfhi(g.z) + bfhi(t.z); o1[2] = o1[2] * bflo(g.w) + bflo(t.w); o1[3] = o1[3] * bfhi(g.w) + bfhi(t.w);
;                     *(u32x4*)(O + (size_t)row * D + c) = pack8(o0, o1);
;                 }
;             }
.LBB0_922:
	s_waitcnt vmcnt(14)
	v_lshlrev_b32_e32 v148, 16, v144
	v_and_b32_e32 v149, 0xffff0000, v144
	v_lshlrev_b32_e32 v154, 16, v156
	v_and_b32_e32 v155, 0xffff0000, v156
	v_pk_fma_f32 v[126:127], v[126:127], v[148:149], v[154:155]
	v_lshlrev_b32_e32 v148, 16, v145
	v_and_b32_e32 v149, 0xffff0000, v145
	v_lshlrev_b32_e32 v154, 16, v157
	v_and_b32_e32 v155, 0xffff0000, v157
	v_pk_fma_f32 v[128:129], v[128:129], v[148:149], v[154:155]
	v_lshlrev_b32_e32 v148, 16, v146
	v_and_b32_e32 v149, 0xffff0000, v146
	v_lshlrev_b32_e32 v154, 16, v158
	v_and_b32_e32 v155, 0xffff0000, v158
	v_pk_fma_f32 v[122:123], v[122:123], v[148:149], v[154:155]
	v_lshlrev_b32_e32 v148, 16, v147
	v_and_b32_e32 v149, 0xffff0000, v147
	v_lshlrev_b32_e32 v154, 16, v159
	v_and_b32_e32 v155, 0xffff0000, v159
	v_pk_fma_f32 v[124:125], v[124:125], v[148:149], v[154:155]
	v_cvt_pk_bf16_f32 v144, v126, v127
	v_cvt_pk_bf16_f32 v145, v128, v129
	v_cvt_pk_bf16_f32 v146, v122, v123
	v_cvt_pk_bf16_f32 v147, v124, v125
	global_store_dwordx4 v139, v[144:147], s[84:85] sc1
	s_waitcnt vmcnt(13)
	v_lshlrev_b32_e32 v148, 16, v160
	v_and_b32_e32 v149, 0xffff0000, v160
	v_lshlrev_b32_e32 v154, 16, v164
	v_and_b32_e32 v155, 0xffff0000, v164
	v_pk_fma_f32 v[118:119], v[118:119], v[148:149], v[154:155]
	v_lshlrev_b32_e32 v148, 16, v161
	v_and_b32_e32 v149, 0xffff0000, v161
	v_lshlrev_b32_e32 v154, 16, v165
	v_and_b32_e32 v155, 0xffff0000, v165
	v_pk_fma_f32 v[120:121], v[120:121], v[148:149], v[154:155]
	v_lshlrev_b32_e32 v148, 16, v162
	v_and_b32_e32 v149, 0xffff0000, v162
	v_lshlrev_b32_e32 v154, 16, v166
	v_and_b32_e32 v155, 0xffff0000, v166
	v_pk_fma_f32 v[114:115], v[114:115], v[148:149], v[154:155]
	v_lshlrev_b32_e32 v148, 16, v163
	v_and_b32_e32 v149, 0xffff0000, v163
	v_lshlrev_b32_e32 v154, 16, v167
	v_and_b32_e32 v155, 0xffff0000, v167
	v_pk_fma_f32 v[116:117], v[116:117], v[148:149], v[154:155]
	v_cvt_pk_bf16_f32 v160, v118, v119
	v_cvt_pk_bf16_f32 v161, v120, v121
	v_cvt_pk_bf16_f32 v162, v114, v115
	v_cvt_pk_bf16_f32 v163, v116, v117
	global_store_dwordx4 v139, v[160:163], s[84:85] offset:256 sc1
	s_nop 1
	v_add_u32_e32 v140, 0xd0000, v138
	v_add_u32_e32 v141, 0x40000, v139
	global_load_dwordx4 v[144:147], v140, s[72:73]
	global_load_dwordx4 v[156:159], v141, s[36:37]
	global_load_dwordx4 v[160:163], v140, s[72:73] offset:256
	global_load_dwordx4 v[164:167], v141, s[36:37] offset:256
	v_add_u32_e32 v141, 0x8000, v139
	s_waitcnt vmcnt(16)
	v_lshlrev_b32_e32 v148, 16, v168
	v_and_b32_e32 v149, 0xffff0000, v168
	v_lshlrev_b32_e32 v154, 16, v172
	v_and_b32_e32 v155, 0xffff0000, v172
	v_pk_fma_f32 v[110:111], v[110:111], v[148:149], v[154:155]
	v_lshlrev_b32_e32 v148, 16, v169
	v_and_b32_e32 v149, 0xffff0000, v169
	v_lshlrev_b32_e32 v154, 16, v173
	v_and_b32_e32 v155, 0xffff0000, v173
	v_pk_fma_f32 v[112:113], v[112:113], v[148:149], v[154:155]
	v_lshlrev_b32_e32 v148, 16, v170
	v_and_b32_e32 v149, 0xffff0000, v170
	v_lshlrev_b32_e32 v154, 16, v174
	v_and_b32_e32 v155, 0xffff0000, v174
	v_pk_fma_f32 v[106:107], v[106:107], v[148:149], v[154:155]
	v_lshlrev_b32_e32 v148, 16, v171
	v_and_b32_e32 v149, 0xffff0000, v171
	v_lshlrev_b32_e32 v154, 16, v175
	v_and_b32_e32 v155, 0xffff0000, v175
	v_pk_fma_f32 v[108:109], v[108:109], v[148:149], v[154:155]
	v_cvt_pk_bf16_f32 v168, v110, v111
	v_cvt_pk_bf16_f32 v169, v112, v113
	v_cvt_pk_bf16_f32 v170, v106, v107
	v_cvt_pk_bf16_f32 v171, v108, v109
	global_store_dwordx4 v141, v[168:171], s[84:85] sc1
	s_waitcnt vmcnt(15)
	v_lshlrev_b32_e32 v148, 16, v176
	v_and_b32_e32 v149, 0xffff0000, v176
	v_lshlrev_b32_e32 v154, 16, v180
	v_and_b32_e32 v155, 0xffff0000, v180
	v_pk_fma_f32 v[102:103], v[102:103], v[148:149], v[154:155]
	v_lshlrev_b32_e32 v148, 16, v177
	v_and_b32_e32 v149, 0xffff0000, v177
	v_lshlrev_b32_e32 v154, 16, v181
	v_and_b32_e32 v155, 0xffff0000, v181
	v_pk_fma_f32 v[104:105], v[104:105], v[148:149], v[154:155]
	v_lshlrev_b32_e32 v148, 16, v178
	v_and_b32_e32 v149, 0xffff0000, v178
	v_lshlrev_b32_e32 v154, 16, v182
	v_and_b32_e32 v155, 0xffff0000, v182
	v_pk_fma_f32 v[98:99], v[98:99], v[148:149], v[154:155]
	v_lshlrev_b32_e32 v148, 16, v179
	v_and_b32_e32 v149, 0xffff0000, v179
	v_lshlrev_b32_e32 v154, 16, v183
	v_and_b32_e32 v155, 0xffff0000, v183
	v_pk_fma_f32 v[100:101], v[100:101], v[148:149], v[154:155]
	v_cvt_pk_bf16_f32 v176, v102, v103
	v_cvt_pk_bf16_f32 v177, v104, v105
	v_cvt_pk_bf16_f32 v178, v98, v99
	v_cvt_pk_bf16_f32 v179, v100, v101
	global_store_dwordx4 v141, v[176:179], s[84:85] offset:256 sc1
	s_nop 1
	v_add_u32_e32 v140, 0xea000, v138
	v_add_u32_e32 v141, 0x48000, v139
	global_load_dwordx4 v[168:171], v140, s[72:73]
	global_load_dwordx4 v[172:175], v141, s[36:37]
	global_load_dwordx4 v[176:179], v140, s[72:73] offset:256
	global_load_dwordx4 v[180:183], v141, s[36:37] offset:256
	v_add_u32_e32 v141, 0x10000, v139
	s_waitcnt vmcnt(18)
	v_lshlrev_b32_e32 v148, 16, v184
	v_and_b32_e32 v149, 0xffff0000, v184
	v_lshlrev_b32_e32 v154, 16, v188
	v_and_b32_e32 v155, 0xffff0000, v188
	v_pk_fma_f32 v[94:95], v[94:95], v[148:149], v[154:155]
	v_lshlrev_b32_e32 v148, 16, v185
	v_and_b32_e32 v149, 0xffff0000, v185
	v_lshlrev_b32_e32 v154, 16, v189
	v_and_b32_e32 v155, 0xffff0000, v189
	v_pk_fma_f32 v[96:97], v[96:97], v[148:149], v[154:155]
	v_lshlrev_b32_e32 v148, 16, v186
	v_and_b32_e32 v149, 0xffff0000, v186
	v_lshlrev_b32_e32 v154, 16, v190
	v_and_b32_e32 v155, 0xffff0000, v190
	v_pk_fma_f32 v[90:91], v[90:91], v[148:149], v[154:155]
	v_lshlrev_b32_e32 v148, 16, v187
	v_and_b32_e32 v149, 0xffff0000, v187
	v_lshlrev_b32_e32 v154, 16, v191
	v_and_b32_e32 v155, 0xffff0000, v191
	v_pk_fma_f32 v[92:93], v[92:93], v[148:149], v[154:155]
	v_cvt_pk_bf16_f32 v184, v94, v95
	v_cvt_pk_bf16_f32 v185, v96, v97
	v_cvt_pk_bf16_f32 v186, v90, v91
	v_cvt_pk_bf16_f32 v187, v92, v93
	global_store_dwordx4 v141, v[184:187], s[84:85] sc1
	s_waitcnt vmcnt(17)
; __device__ __forceinline__ float bflo(unsigned w) { return __uint_as_float(w << 16); }
; __device__ __forceinline__ float bfhi(unsigned w) { return __uint_as_float(w & 0xffff0000u); }
; __device__ __forceinline__ u32x4 pack8(const f32x4 a, const f32x4 b) { u32x4 w; w.x = cvt_pk_bf16(a[0], a[1]); w.y = cvt_pk_bf16(a[2], a[3]); w.z = cvt_pk_bf16(b[0], b[1]); w.w = cvt_pk_bf16(b[2], b[3]); return w; }
;     __device__ __forceinline__ void operator()(const f32x4 (&acc)[2][2][4][2], const Unit& u, int wr, int wc, int fr, int fq) const {
;         const int row0 = u.pm * 256 + wr * 64 + fr, col0 = u.pn * 256 + wc * 32 + 8 * fq;
; #pragma unroll
;         for (int ai = 0; ai < 2; ++ai)
; #pragma unroll
;             for (int m = 0; m < 4; ++m) {
;                 const int row = row0 + ai * 128 + m * 16;
; #pragma unroll
;                 for (int bj = 0; bj < 2; ++bj) {
;                     const int c = col0 + bj * 128;
;                     const u32x4 g = *(const u32x4*)(G + (size_t)row * P2W + c);
;                     const u32x4 t = *(const u32x4*)(T + (size_t)row * D + c);
;                     f32x4 o0 = acc[ai][bj][m][0], o1 = acc[ai][bj][m][1];
;                     o0[0] = o0[0] * bflo(g.x) + bflo(t.x); o0[1] = o0[1] * bfhi(g.x) + bfhi(t.x); o0[2] = o0[2] * bflo(g.y) + bflo(t.y); o0[3] = o0[3] * bfhi(g.y) + bfhi(t.y);
;                     o1[0] = o1[0] * bflo(g.z) + bflo(t.z); o1[1] = o1[1] * bfhi(g.z) + bfhi(t.z); o1[2] = o1[2] * bflo(g.w) + bflo(t.w); o1[3] = o1[3] * bfhi(g.w) + bfhi(t.w);
;                     *(u32x4*)(O + (size_t)row * D + c) = pack8(o0, o1);
;                 }
;             }
	v_lshlrev_b32_e32 v148, 16, v192
	v_and_b32_e32 v149, 0xffff0000, v192
	v_lshlrev_b32_e32 v154, 16, v196
	v_and_b32_e32 v155, 0xffff0000, v196
	v_pk_fma_f32 v[86:87], v[86:87], v[148:149], v[154:155]
	v_lshlrev_b32_e32 v148, 16, v193
	v_and_b32_e32 v149, 0xffff0000, v193
	v_lshlrev_b32_e32 v154, 16, v197
	v_and_b32_e32 v155, 0xffff0000, v197
	v_pk_fma_f32 v[88:89], v[88:89], v[148:149], v[154:155]
	v_lshlrev_b32_e32 v148, 16, v194
	v_and_b32_e32 v149, 0xffff0000, v194
	v_lshlrev_b32_e32 v154, 16, v198
	v_and_b32_e32 v155, 0xffff0000, v198
	v_pk_fma_f32 v[82:83], v[82:83], v[148:149], v[154:155]
	v_lshlrev_b32_e32 v148, 16, v195
	v_and_b32_e32 v149, 0xffff0000, v195
	v_lshlrev_b32_e32 v154, 16, v199
	v_and_b32_e32 v155, 0xffff0000, v199
	v_pk_fma_f32 v[84:85], v[84:85], v[148:149], v[154:155]
	v_cvt_pk_bf16_f32 v192, v86, v87
	v_cvt_pk_bf16_f32 v193, v88, v89
	v_cvt_pk_bf16_f32 v194, v82, v83
	v_cvt_pk_bf16_f32 v195, v84, v85
	global_store_dwordx4 v141, v[192:195], s[84:85] offset:256 sc1
	s_nop 1
	v_add_u32_e32 v140, 0x104000, v138
	v_add_u32_e32 v141, 0x50000, v139
	global_load_dwordx4 v[184:187], v140, s[72:73]
	global_load_dwordx4 v[188:191], v141, s[36:37]
	global_load_dwordx4 v[192:195], v140, s[72:73] offset:256
	global_load_dwordx4 v[196:199], v141, s[36:37] offset:256
	v_add_u32_e32 v141, 0x18000, v139
	s_waitcnt vmcnt(20)
	v_lshlrev_b32_e32 v148, 16, v200
	v_and_b32_e32 v149, 0xffff0000, v200
	v_lshlrev_b32_e32 v154, 16, v224
	v_and_b32_e32 v155, 0xffff0000, v224
	v_pk_fma_f32 v[78:79], v[78:79], v[148:149], v[154:155]
	v_lshlrev_b32_e32 v148, 16, v201
	v_and_b32_e32 v149, 0xffff0000, v201
	v_lshlrev_b32_e32 v154, 16, v225
	v_and_b32_e32 v155, 0xffff0000, v225
	v_pk_fma_f32 v[80:81], v[80:81], v[148:149], v[154:155]
	v_lshlrev_b32_e32 v148, 16, v202
	v_and_b32_e32 v149, 0xffff0000, v202
	v_lshlrev_b32_e32 v154, 16, v226
	v_and_b32_e32 v155, 0xffff0000, v226
	v_pk_fma_f32 v[74:75], v[74:75], v[148:149], v[154:155]
	v_lshlrev_b32_e32 v148, 16, v203
	v_and_b32_e32 v149, 0xffff0000, v203
	v_lshlrev_b32_e32 v154, 16, v227
	v_and_b32_e32 v155, 0xffff0000, v227
	v_pk_fma_f32 v[76:77], v[76:77], v[148:149], v[154:155]
	v_cvt_pk_bf16_f32 v200, v78, v79
	v_cvt_pk_bf16_f32 v201, v80, v81
	v_cvt_pk_bf16_f32 v202, v74, v75
	v_cvt_pk_bf16_f32 v203, v76, v77
	global_store_dwordx4 v141, v[200:203], s[84:85] sc1
	s_waitcnt vmcnt(19)
	v_lshlrev_b32_e32 v148, 16, v228
	v_and_b32_e32 v149, 0xffff0000, v228
	v_lshlrev_b32_e32 v154, 16, v232
	v_and_b32_e32 v155, 0xffff0000, v232
	v_pk_fma_f32 v[70:71], v[70:71], v[148:149], v[154:155]
	v_lshlrev_b32_e32 v148, 16, v229
	v_and_b32_e32 v149, 0xffff0000, v229
	v_lshlrev_b32_e32 v154, 16, v233
	v_and_b32_e32 v155, 0xffff0000, v233
	v_pk_fma_f32 v[72:73], v[72:73], v[148:149], v[154:155]
	v_lshlrev_b32_e32 v148, 16, v230
	v_and_b32_e32 v149, 0xffff0000, v230
	v_lshlrev_b32_e32 v154, 16, v234
	v_and_b32_e32 v155, 0xffff0000, v234
	v_pk_fma_f32 v[66:67], v[66:67], v[148:149], v[154:155]
	v_lshlrev_b32_e32 v148, 16, v231
	v_and_b32_e32 v149, 0xffff0000, v231
	v_lshlrev_b32_e32 v154, 16, v235
	v_and_b32_e32 v155, 0xffff0000, v235
	v_pk_fma_f32 v[68:69], v[68:69], v[148:149], v[154:155]
	v_cvt_pk_bf16_f32 v228, v70, v71
	v_cvt_pk_bf16_f32 v229, v72, v73
	v_cvt_pk_bf16_f32 v230, v66, v67
	v_cvt_pk_bf16_f32 v231, v68, v69
	global_store_dwordx4 v141, v[228:231], s[84:85] offset:256 sc1
	s_nop 1
	v_add_u32_e32 v140, 0x11e000, v138
	v_add_u32_e32 v141, 0x58000, v139
	global_load_dwordx4 v[200:203], v140, s[72:73]
	global_load_dwordx4 v[224:227], v141, s[36:37]
	global_load_dwordx4 v[228:231], v140, s[72:73] offset:256
	global_load_dwordx4 v[232:235], v141, s[36:37] offset:256
	v_add_u32_e32 v141, 0x40000, v139
	s_waitcnt vmcnt(20)
	v_lshlrev_b32_e32 v148, 16, v144
	v_and_b32_e32 v149, 0xffff0000, v144
	v_lshlrev_b32_e32 v154, 16, v156
	v_and_b32_e32 v155, 0xffff0000, v156
	v_pk_fma_f32 v[62:63], v[62:63], v[148:149], v[154:155]
	v_lshlrev_b32_e32 v148, 16, v145
	v_and_b32_e32 v149, 0xffff0000, v145
	v_lshlrev_b32_e32 v154, 16, v157
	v_and_b32_e32 v155, 0xffff0000, v157
	v_pk_fma_f32 v[64:65], v[64:65], v[148:149], v[154:155]
	v_lshlrev_b32_e32 v148, 16, v146
	v_and_b32_e32 v149, 0xffff0000, v146
	v_lshlrev_b32_e32 v154, 16, v158
	v_and_b32_e32 v155, 0xffff0000, v158
	v_pk_fma_f32 v[58:59], v[58:59], v[148:149], v[154:155]
	v_lshlrev_b32_e32 v148, 16, v147
	v_and_b32_e32 v149, 0xffff0000, v147
	v_lshlrev_b32_e32 v154, 16, v159
	v_and_b32_e32 v155, 0xffff0000, v159
	v_pk_fma_f32 v[60:61], v[60:61], v[148:149], v[154:155]
	v_cvt_pk_bf16_f32 v144, v62, v63
	v_cvt_pk_bf16_f32 v145, v64, v65
	v_cvt_pk_bf16_f32 v146, v58, v59
	v_cvt_pk_bf16_f32 v147, v60, v61
	global_store_dwordx4 v141, v[144:147], s[84:85] sc1
	s_waitcnt vmcnt(19)
	v_lshlrev_b32_e32 v148, 16, v160
	v_and_b32_e32 v149, 0xffff0000, v160
	v_lshlrev_b32_e32 v154, 16, v164
	v_and_b32_e32 v155, 0xffff0000, v164
	v_pk_fma_f32 v[54:55], v[54:55], v[148:149], v[154:155]
	v_lshlrev_b32_e32 v148, 16, v161
	v_and_b32_e32 v149, 0xffff0000, v161
	v_lshlrev_b32_e32 v154, 16, v165
	v_and_b32_e32 v155, 0xffff0000, v165
	v_pk_fma_f32 v[56:57], v[56:57], v[148:149], v[154:155]
	v_lshlrev_b32_e32 v148, 16, v162
	v_and_b32_e32 v149, 0xffff0000, v162
	v_lshlrev_b32_e32 v154, 16, v166
	v_and_b32_e32 v155, 0xffff0000, v166
	v_pk_fma_f32 v[50:51], v[50:51], v[148:149], v[154:155]
	v_lshlrev_b32_e32 v148, 16, v163
	v_and_b32_e32 v149, 0xffff0000, v163
	v_lshlrev_b32_e32 v154, 16, v167
	v_and_b32_e32 v155, 0xffff0000, v167
	v_pk_fma_f32 v[52:53], v[52:53], v[148:149], v[154:155]
	v_cvt_pk_bf16_f32 v160, v54, v55
	v_cvt_pk_bf16_f32 v161, v56, v57
	v_cvt_pk_bf16_f32 v162, v50, v51
	v_cvt_pk_bf16_f32 v163, v52, v53
	global_store_dwordx4 v141, v[160:163], s[84:85] offset:256 sc1
	v_add_u32_e32 v141, 0x48000, v139
	s_waitcnt vmcnt(16)
; __device__ __forceinline__ float bflo(unsigned w) { return __uint_as_float(w << 16); }
; __device__ __forceinline__ float bfhi(unsigned w) { return __uint_as_float(w & 0xffff0000u); }
; __device__ __forceinline__ u32x4 pack8(const f32x4 a, const f32x4 b) { u32x4 w; w.x = cvt_pk_bf16(a[0], a[1]); w.y = cvt_pk_bf16(a[2], a[3]); w.z = cvt_pk_bf16(b[0], b[1]); w.w = cvt_pk_bf16(b[2], b[3]); return w; }
;     __device__ __forceinline__ void operator()(const f32x4 (&acc)[2][2][4][2], const Unit& u, int wr, int wc, int fr, int fq) const {
;         const int row0 = u.pm * 256 + wr * 64 + fr, col0 = u.pn * 256 + wc * 32 + 8 * fq;
; #pragma unroll
;         for (int ai = 0; ai < 2; ++ai)
; #pragma unroll
;             for (int m = 0; m < 4; ++m) {
;                 const int row = row0 + ai * 128 + m * 16;
; #pragma unroll
;                 for (int bj = 0; bj < 2; ++bj) {
;                     const int c = col0 + bj * 128;
;                     const u32x4 g = *(const u32x4*)(G + (size_t)row * P2W + c);
;                     const u32x4 t = *(const u32x4*)(T + (size_t)row * D + c);
;                     f32x4 o0 = acc[ai][bj][m][0], o1 = acc[ai][bj][m][1];
;                     o0[0] = o0[0] * bflo(g.x) + bflo(t.x); o0[1] = o0[1] * bfhi(g.x) + bfhi(t.x); o0[2] = o0[2] * bflo(g.y) + bflo(t.y); o0[3] = o0[3] * bfhi(g.y) + bfhi(t.y);
;                     o1[0] = o1[0] * bflo(g.z) + bflo(t.z); o1[1] = o1[1] * bfhi(g.z) + bfhi(t.z); o1[2] = o1[2] * bflo(g.w) + bflo(t.w); o1[3] = o1[3] * bfhi(g.w) + bfhi(t.w);
;                     *(u32x4*)(O + (size_t)row * D + c) = pack8(o0, o1);
;                 }
;             }
	v_lshlrev_b32_e32 v148, 16, v168
	v_and_b32_e32 v149, 0xffff0000, v168
	v_lshlrev_b32_e32 v154, 16, v172
	v_and_b32_e32 v155, 0xffff0000, v172
	v_pk_fma_f32 v[46:47], v[46:47], v[148:149], v[154:155]
	v_lshlrev_b32_e32 v148, 16, v169
	v_and_b32_e32 v149, 0xffff0000, v169
	v_lshlrev_b32_e32 v154, 16, v173
	v_and_b32_e32 v155, 0xffff0000, v173
	v_pk_fma_f32 v[48:49], v[48:49], v[148:149], v[154:155]
	v_lshlrev_b32_e32 v148, 16, v170
	v_and_b32_e32 v149, 0xffff0000, v170
	v_lshlrev_b32_e32 v154, 16, v174
	v_and_b32_e32 v155, 0xffff0000, v174
	v_pk_fma_f32 v[42:43], v[42:43], v[148:149], v[154:155]
	v_lshlrev_b32_e32 v148, 16, v171
	v_and_b32_e32 v149, 0xffff0000, v171
	v_lshlrev_b32_e32 v154, 16, v175
	v_and_b32_e32 v155, 0xffff0000, v175
	v_pk_fma_f32 v[44:45], v[44:45], v[148:149], v[154:155]
	v_cvt_pk_bf16_f32 v168, v46, v47
	v_cvt_pk_bf16_f32 v169, v48, v49
	v_cvt_pk_bf16_f32 v170, v42, v43
	v_cvt_pk_bf16_f32 v171, v44, v45
	global_store_dwordx4 v141, v[168:171], s[84:85] sc1
	s_waitcnt vmcnt(15)
	v_lshlrev_b32_e32 v148, 16, v176
	v_and_b32_e32 v149, 0xffff0000, v176
	v_lshlrev_b32_e32 v154, 16, v180
	v_and_b32_e32 v155, 0xffff0000, v180
	v_pk_fma_f32 v[38:39], v[38:39], v[148:149], v[154:155]
	v_lshlrev_b32_e32 v148, 16, v177
	v_and_b32_e32 v149, 0xffff0000, v177
	v_lshlrev_b32_e32 v154, 16, v181
	v_and_b32_e32 v155, 0xffff0000, v181
	v_pk_fma_f32 v[40:41], v[40:41], v[148:149], v[154:155]
	v_lshlrev_b32_e32 v148, 16, v178
	v_and_b32_e32 v149, 0xffff0000, v178
	v_lshlrev_b32_e32 v154, 16, v182
	v_and_b32_e32 v155, 0xffff0000, v182
	v_pk_fma_f32 v[34:35], v[34:35], v[148:149], v[154:155]
	v_lshlrev_b32_e32 v148, 16, v179
	v_and_b32_e32 v149, 0xffff0000, v179
	v_lshlrev_b32_e32 v154, 16, v183
	v_and_b32_e32 v155, 0xffff0000, v183
	v_pk_fma_f32 v[36:37], v[36:37], v[148:149], v[154:155]
	v_cvt_pk_bf16_f32 v176, v38, v39
	v_cvt_pk_bf16_f32 v177, v40, v41
	v_cvt_pk_bf16_f32 v178, v34, v35
	v_cvt_pk_bf16_f32 v179, v36, v37
	global_store_dwordx4 v141, v[176:179], s[84:85] offset:256 sc1
	v_add_u32_e32 v141, 0x50000, v139
	s_waitcnt vmcnt(12)
	v_lshlrev_b32_e32 v148, 16, v184
	v_and_b32_e32 v149, 0xffff0000, v184
	v_lshlrev_b32_e32 v154, 16, v188
	v_and_b32_e32 v155, 0xffff0000, v188
	v_pk_fma_f32 v[30:31], v[30:31], v[148:149], v[154:155]
	v_lshlrev_b32_e32 v148, 16, v185
	v_and_b32_e32 v149, 0xffff0000, v185
	v_lshlrev_b32_e32 v154, 16, v189
	v_and_b32_e32 v155, 0xffff0000, v189
	v_pk_fma_f32 v[32:33], v[32:33], v[148:149], v[154:155]
	v_lshlrev_b32_e32 v148, 16, v186
	v_and_b32_e32 v149, 0xffff0000, v186
	v_lshlrev_b32_e32 v154, 16, v190
	v_and_b32_e32 v155, 0xffff0000, v190
	v_pk_fma_f32 v[26:27], v[26:27], v[148:149], v[154:155]
	v_lshlrev_b32_e32 v148, 16, v187
	v_and_b32_e32 v149, 0xffff0000, v187
	v_lshlrev_b32_e32 v154, 16, v191
	v_and_b32_e32 v155, 0xffff0000, v191
	v_pk_fma_f32 v[28:29], v[28:29], v[148:149], v[154:155]
	v_cvt_pk_bf16_f32 v184, v30, v31
	v_cvt_pk_bf16_f32 v185, v32, v33
	v_cvt_pk_bf16_f32 v186, v26, v27
	v_cvt_pk_bf16_f32 v187, v28, v29
	global_store_dwordx4 v141, v[184:187], s[84:85] sc1
	s_waitcnt vmcnt(11)
	v_lshlrev_b32_e32 v148, 16, v192
	v_and_b32_e32 v149, 0xffff0000, v192
	v_lshlrev_b32_e32 v154, 16, v196
	v_and_b32_e32 v155, 0xffff0000, v196
	v_pk_fma_f32 v[22:23], v[22:23], v[148:149], v[154:155]
	v_lshlrev_b32_e32 v148, 16, v193
	v_and_b32_e32 v149, 0xffff0000, v193
	v_lshlrev_b32_e32 v154, 16, v197
	v_and_b32_e32 v155, 0xffff0000, v197
	v_pk_fma_f32 v[24:25], v[24:25], v[148:149], v[154:155]
	v_lshlrev_b32_e32 v148, 16, v194
	v_and_b32_e32 v149, 0xffff0000, v194
	v_lshlrev_b32_e32 v154, 16, v198
	v_and_b32_e32 v155, 0xffff0000, v198
	v_pk_fma_f32 v[18:19], v[18:19], v[148:149], v[154:155]
	v_lshlrev_b32_e32 v148, 16, v195
	v_and_b32_e32 v149, 0xffff0000, v195
	v_lshlrev_b32_e32 v154, 16, v199
	v_and_b32_e32 v155, 0xffff0000, v199
	v_pk_fma_f32 v[20:21], v[20:21], v[148:149], v[154:155]
	v_cvt_pk_bf16_f32 v192, v22, v23
	v_cvt_pk_bf16_f32 v193, v24, v25
	v_cvt_pk_bf16_f32 v194, v18, v19
	v_cvt_pk_bf16_f32 v195, v20, v21
	global_store_dwordx4 v141, v[192:195], s[84:85] offset:256 sc1
	v_add_u32_e32 v141, 0x58000, v139
	s_waitcnt vmcnt(8)
	v_lshlrev_b32_e32 v148, 16, v200
	v_and_b32_e32 v149, 0xffff0000, v200
	v_lshlrev_b32_e32 v154, 16, v224
	v_and_b32_e32 v155, 0xffff0000, v224
	v_pk_fma_f32 v[14:15], v[14:15], v[148:149], v[154:155]
	v_lshlrev_b32_e32 v148, 16, v201
	v_and_b32_e32 v149, 0xffff0000, v201
	v_lshlrev_b32_e32 v154, 16, v225
	v_and_b32_e32 v155, 0xffff0000, v225
	v_pk_fma_f32 v[16:17], v[16:17], v[148:149], v[154:155]
	v_lshlrev_b32_e32 v148, 16, v202
	v_and_b32_e32 v149, 0xffff0000, v202
	v_lshlrev_b32_e32 v154, 16, v226
	v_and_b32_e32 v155, 0xffff0000, v226
	v_pk_fma_f32 v[10:11], v[10:11], v[148:149], v[154:155]
	v_lshlrev_b32_e32 v148, 16, v203
	v_and_b32_e32 v149, 0xffff0000, v203
	v_lshlrev_b32_e32 v154, 16, v227
	v_and_b32_e32 v155, 0xffff0000, v227
	v_pk_fma_f32 v[12:13], v[12:13], v[148:149], v[154:155]
	v_cvt_pk_bf16_f32 v200, v14, v15
	v_cvt_pk_bf16_f32 v201, v16, v17
	v_cvt_pk_bf16_f32 v202, v10, v11
	v_cvt_pk_bf16_f32 v203, v12, v13
	global_store_dwordx4 v141, v[200:203], s[84:85] sc1
	s_waitcnt vmcnt(7)
	v_lshlrev_b32_e32 v148, 16, v228
	v_and_b32_e32 v149, 0xffff0000, v228
	v_lshlrev_b32_e32 v154, 16, v232
	v_and_b32_e32 v155, 0xffff0000, v232
	v_pk_fma_f32 v[6:7], v[6:7], v[148:149], v[154:155]
	v_lshlrev_b32_e32 v148, 16, v229
	v_and_b32_e32 v149, 0xffff0000, v229
	v_lshlrev_b32_e32 v154, 16, v233
	v_and_b32_e32 v155, 0xffff0000, v233
	v_pk_fma_f32 v[8:9], v[8:9], v[148:149], v[154:155]
	v_lshlrev_b32_e32 v148, 16, v230
	v_and_b32_e32 v149, 0xffff0000, v230
	v_lshlrev_b32_e32 v154, 16, v234
	v_and_b32_e32 v155, 0xffff0000, v234
	v_pk_fma_f32 v[2:3], v[2:3], v[148:149], v[154:155]
	v_lshlrev_b32_e32 v148, 16, v231
	v_and_b32_e32 v149, 0xffff0000, v231
	v_lshlrev_b32_e32 v154, 16, v235
	v_and_b32_e32 v155, 0xffff0000, v235
	v_pk_fma_f32 v[4:5], v[4:5], v[148:149], v[154:155]
	v_cvt_pk_bf16_f32 v228, v6, v7
	v_cvt_pk_bf16_f32 v229, v8, v9
	v_cvt_pk_bf16_f32 v230, v2, v3
	v_cvt_pk_bf16_f32 v231, v4, v5
	global_store_dwordx4 v141, v[228:231], s[84:85] offset:256 sc1
	s_mov_b64 s[10:11], -1
	s_and_b64 vcc, exec, s[2:3]
	s_cbranch_vccnz .LBB0_907
	s_andn2_b64 vcc, exec, s[0:1]
	s_cbranch_vccnz .LBB0_906
	s_barrier
	s_branch .LBB0_906

; __device__ __forceinline__ float bflo(unsigned w) { return __uint_as_float(w << 16); }
; __device__ __forceinline__ float bfhi(unsigned w) { return __uint_as_float(w & 0xffff0000u); }
; __device__ __forceinline__ u32x4 pack8(const f32x4 a, const f32x4 b) { u32x4 w; w.x = cvt_pk_bf16(a[0], a[1]); w.y = cvt_pk_bf16(a[2], a[3]); w.z = cvt_pk_bf16(b[0], b[1]); w.w = cvt_pk_bf16(b[2], b[3]); return w; }
;     __device__ __forceinline__ void operator()(const f32x4 (&acc)[2][2][4][2], const Unit& u, int wr, int wc, int fr, int fq) const {
;         const int row0 = u.pm * 256 + wr * 64 + fr, col0 = u.pn * 256 + wc * 32 + 8 * fq;
; #pragma unroll
;         for (int ai = 0; ai < 2; ++ai)
; #pragma unroll
;             for (int m = 0; m < 4; ++m) {
;                 const int row = row0 + ai * 128 + m * 16; float p = 0.f;
; #pragma unroll
;                 for (int bj = 0; bj < 2; ++bj) {
;                     const size_t off = (size_t)row * D + col0 + bj * 128;
;                     const u32x4 xx = *(const u32x4*)(xb + off);
;                     const f32x4 x0 = (f32x4){bflo(xx.x), bfhi(xx.x), bflo(xx.y), bfhi(xx.y)}, x1 = (f32x4){bflo(xx.z), bfhi(xx.z), bflo(xx.w), bfhi(xx.w)};
;                     const f32x4 y0 = x0 + acc[ai][bj][m][0] * scale, y1 = x1 + acc[ai][bj][m][1] * scale;
;                     *(u32x4*)(xb + off) = pack8(y0, y1);
;                     const f32x4 q = y0 * y0 + y1 * y1; p += (q[0] + q[1]) + (q[2] + q[3]);
;                 }
;                 p += __shfl_xor(p, 16); p += __shfl_xor(p, 32);
;                 if (fq == 0) ssn[(size_t)row * 16 + u.pn * 4 + wc] = p;
;             }
.LBB0_1053:
	s_waitcnt vmcnt(15)
	v_lshlrev_b32_e32 v144, 16, v152
	v_and_b32_e32 v145, 0xffff0000, v152
	v_lshlrev_b32_e32 v146, 16, v153
	v_and_b32_e32 v147, 0xffff0000, v153
	v_pk_add_f32 v[126:127], v[126:127], v[144:145]
	v_pk_add_f32 v[128:129], v[128:129], v[146:147]
	v_lshlrev_b32_e32 v144, 16, v154
	v_and_b32_e32 v145, 0xffff0000, v154
	v_lshlrev_b32_e32 v146, 16, v155
	v_and_b32_e32 v147, 0xffff0000, v155
	v_pk_add_f32 v[122:123], v[122:123], v[144:145]
	v_pk_add_f32 v[124:125], v[124:125], v[146:147]
	v_cvt_pk_bf16_f32 v152, v126, v127
	v_cvt_pk_bf16_f32 v153, v128, v129
	v_cvt_pk_bf16_f32 v154, v122, v123
	v_cvt_pk_bf16_f32 v155, v124, v125
	global_store_dwordx4 v138, v[152:155], s[34:35] sc1
	v_pk_mul_f32 v[126:127], v[126:127], v[126:127]
	v_pk_fma_f32 v[126:127], v[128:129], v[128:129], v[126:127]
	v_pk_fma_f32 v[126:127], v[122:123], v[122:123], v[126:127]
	v_pk_fma_f32 v[126:127], v[124:125], v[124:125], v[126:127]
	s_waitcnt vmcnt(15)
	v_lshlrev_b32_e32 v144, 16, v156
	v_and_b32_e32 v145, 0xffff0000, v156
	v_lshlrev_b32_e32 v146, 16, v157
	v_and_b32_e32 v147, 0xffff0000, v157
	v_pk_add_f32 v[118:119], v[118:119], v[144:145]
	v_pk_add_f32 v[120:121], v[120:121], v[146:147]
	v_lshlrev_b32_e32 v144, 16, v158
	v_and_b32_e32 v145, 0xffff0000, v158
	v_lshlrev_b32_e32 v146, 16, v159
	v_and_b32_e32 v147, 0xffff0000, v159
	v_pk_add_f32 v[114:115], v[114:115], v[144:145]
	v_pk_add_f32 v[116:117], v[116:117], v[146:147]
	v_cvt_pk_bf16_f32 v156, v118, v119
	v_cvt_pk_bf16_f32 v157, v120, v121
	v_cvt_pk_bf16_f32 v158, v114, v115
	v_cvt_pk_bf16_f32 v159, v116, v117
	global_store_dwordx4 v138, v[156:159], s[34:35] offset:256 sc1
	v_pk_fma_f32 v[126:127], v[118:119], v[118:119], v[126:127]
	v_pk_fma_f32 v[126:127], v[120:121], v[120:121], v[126:127]
	v_pk_fma_f32 v[126:127], v[114:115], v[114:115], v[126:127]
	v_pk_fma_f32 v[126:127], v[116:117], v[116:117], v[126:127]
	v_add_f32_e32 v126, v126, v127
	v_add_u32_e32 v139, 0x8000, v138
	s_waitcnt vmcnt(15)
	v_lshlrev_b32_e32 v144, 16, v160
	v_and_b32_e32 v145, 0xffff0000, v160
	v_lshlrev_b32_e32 v146, 16, v161
	v_and_b32_e32 v147, 0xffff0000, v161
	v_pk_add_f32 v[110:111], v[110:111], v[144:145]
	v_pk_add_f32 v[112:113], v[112:113], v[146:147]
	v_lshlrev_b32_e32 v144, 16, v162
	v_and_b32_e32 v145, 0xffff0000, v162
	v_lshlrev_b32_e32 v146, 16, v163
	v_and_b32_e32 v147, 0xffff0000, v163
	v_pk_add_f32 v[106:107], v[106:107], v[144:145]
	v_pk_add_f32 v[108:109], v[108:109], v[146:147]
	v_cvt_pk_bf16_f32 v160, v110, v111
	v_cvt_pk_bf16_f32 v161, v112, v113
	v_cvt_pk_bf16_f32 v162, v106, v107
	v_cvt_pk_bf16_f32 v163, v108, v109
	global_store_dwordx4 v139, v[160:163], s[34:35] sc1
	v_pk_mul_f32 v[110:111], v[110:111], v[110:111]
	v_pk_fma_f32 v[110:111], v[112:113], v[112:113], v[110:111]
	v_pk_fma_f32 v[110:111], v[106:107], v[106:107], v[110:111]
	v_pk_fma_f32 v[110:111], v[108:109], v[108:109], v[110:111]
	s_waitcnt vmcnt(15)
	v_lshlrev_b32_e32 v144, 16, v164
	v_and_b32_e32 v145, 0xffff0000, v164
	v_lshlrev_b32_e32 v146, 16, v165
	v_and_b32_e32 v147, 0xffff0000, v165
	v_pk_add_f32 v[102:103], v[102:103], v[144:145]
	v_pk_add_f32 v[104:105], v[104:105], v[146:147]
	v_lshlrev_b32_e32 v144, 16, v166
	v_and_b32_e32 v145, 0xffff0000, v166
	v_lshlrev_b32_e32 v146, 16, v167
	v_and_b32_e32 v147, 0xffff0000, v167
	v_pk_add_f32 v[98:99], v[98:99], v[144:145]
	v_pk_add_f32 v[100:101], v[100:101], v[146:147]
	v_cvt_pk_bf16_f32 v164, v102, v103
	v_cvt_pk_bf16_f32 v165, v104, v105
	v_cvt_pk_bf16_f32 v166, v98, v99
	v_cvt_pk_bf16_f32 v167, v100, v101
	global_store_dwordx4 v139, v[164:167], s[34:35] offset:256 sc1
	v_pk_fma_f32 v[110:111], v[102:103], v[102:103], v[110:111]
	v_pk_fma_f32 v[110:111], v[104:105], v[104:105], v[110:111]
	v_pk_fma_f32 v[110:111], v[98:99], v[98:99], v[110:111]
	v_pk_fma_f32 v[110:111], v[100:101], v[100:101], v[110:111]
	v_add_f32_e32 v110, v110, v111
	v_add_u32_e32 v139, 0x10000, v138
	s_waitcnt vmcnt(15)
	v_lshlrev_b32_e32 v144, 16, v168
	v_and_b32_e32 v145, 0xffff0000, v168
	v_lshlrev_b32_e32 v146, 16, v169
	v_and_b32_e32 v147, 0xffff0000, v169
	v_pk_add_f32 v[94:95], v[94:95], v[144:145]
	v_pk_add_f32 v[96:97], v[96:97], v[146:147]
	v_lshlrev_b32_e32 v144, 16, v170
	v_and_b32_e32 v145, 0xffff0000, v170
	v_lshlrev_b32_e32 v146, 16, v171
	v_and_b32_e32 v147, 0xffff0000, v171
	v_pk_add_f32 v[90:91], v[90:91], v[144:145]
	v_pk_add_f32 v[92:93], v[92:93], v[146:147]
	v_cvt_pk_bf16_f32 v168, v94, v95
	v_cvt_pk_bf16_f32 v169, v96, v97
	v_cvt_pk_bf16_f32 v170, v90, v91
	v_cvt_pk_bf16_f32 v171, v92, v93
	global_store_dwordx4 v139, v[168:171], s[34:35] sc1
	v_pk_mul_f32 v[94:95], v[94:95], v[94:95]
	v_pk_fma_f32 v[94:95], v[96:97], v[96:97], v[94:95]
	v_pk_fma_f32 v[94:95], v[90:91], v[90:91], v[94:95]
	v_pk_fma_f32 v[94:95], v[92:93], v[92:93], v[94:95]
	s_waitcnt vmcnt(15)
	v_lshlrev_b32_e32 v144, 16, v172
	v_and_b32_e32 v145, 0xffff0000, v172
	v_lshlrev_b32_e32 v146, 16, v173
	v_and_b32_e32 v147, 0xffff0000, v173
	v_pk_add_f32 v[86:87], v[86:87], v[144:145]
	v_pk_add_f32 v[88:89], v[88:89], v[146:147]
	v_lshlrev_b32_e32 v144, 16, v174
	v_and_b32_e32 v145, 0xffff0000, v174
	v_lshlrev_b32_e32 v146, 16, v175
	v_and_b32_e32 v147, 0xffff0000, v175
	v_pk_add_f32 v[82:83], v[82:83], v[144:145]
	v_pk_add_f32 v[84:85], v[84:85], v[146:147]
	v_cvt_pk_bf16_f32 v172, v86, v87
	v_cvt_pk_bf16_f32 v173, v88, v89
	v_cvt_pk_bf16_f32 v174, v82, v83
	v_cvt_pk_bf16_f32 v175, v84, v85
	global_store_dwordx4 v139, v[172:175], s[34:35] offset:256 sc1
	v_pk_fma_f32 v[94:95], v[86:87], v[86:87], v[94:95]
	v_pk_fma_f32 v[94:95], v[88:89], v[88:89], v[94:95]
	v_pk_fma_f32 v[94:95], v[82:83], v[82:83], v[94:95]
	v_pk_fma_f32 v[94:95], v[84:85], v[84:85], v[94:95]
	v_add_f32_e32 v94, v94, v95
	v_add_u32_e32 v139, 0x18000, v138
	s_waitcnt vmcnt(15)
; __device__ __forceinline__ float bflo(unsigned w) { return __uint_as_float(w << 16); }
; __device__ __forceinline__ float bfhi(unsigned w) { return __uint_as_float(w & 0xffff0000u); }
; __device__ __forceinline__ u32x4 pack8(const f32x4 a, const f32x4 b) { u32x4 w; w.x = cvt_pk_bf16(a[0], a[1]); w.y = cvt_pk_bf16(a[2], a[3]); w.z = cvt_pk_bf16(b[0], b[1]); w.w = cvt_pk_bf16(b[2], b[3]); return w; }
;     __device__ __forceinline__ void operator()(const f32x4 (&acc)[2][2][4][2], const Unit& u, int wr, int wc, int fr, int fq) const {
;         const int row0 = u.pm * 256 + wr * 64 + fr, col0 = u.pn * 256 + wc * 32 + 8 * fq;
; #pragma unroll
;         for (int ai = 0; ai < 2; ++ai)
; #pragma unroll
;             for (int m = 0; m < 4; ++m) {
;                 const int row = row0 + ai * 128 + m * 16; float p = 0.f;
; #pragma unroll
;                 for (int bj = 0; bj < 2; ++bj) {
;                     const size_t off = (size_t)row * D + col0 + bj * 128;
;                     const u32x4 xx = *(const u32x4*)(xb + off);
;                     const f32x4 x0 = (f32x4){bflo(xx.x), bfhi(xx.x), bflo(xx.y), bfhi(xx.y)}, x1 = (f32x4){bflo(xx.z), bfhi(xx.z), bflo(xx.w), bfhi(xx.w)};
;                     const f32x4 y0 = x0 + acc[ai][bj][m][0] * scale, y1 = x1 + acc[ai][bj][m][1] * scale;
;                     *(u32x4*)(xb + off) = pack8(y0, y1);
;                     const f32x4 q = y0 * y0 + y1 * y1; p += (q[0] + q[1]) + (q[2] + q[3]);
;                 }
;                 p += __shfl_xor(p, 16); p += __shfl_xor(p, 32);
;                 if (fq == 0) ssn[(size_t)row * 16 + u.pn * 4 + wc] = p;
;             }
	v_lshlrev_b32_e32 v144, 16, v176
	v_and_b32_e32 v145, 0xffff0000, v176
	v_lshlrev_b32_e32 v146, 16, v177
	v_and_b32_e32 v147, 0xffff0000, v177
	v_pk_add_f32 v[78:79], v[78:79], v[144:145]
	v_pk_add_f32 v[80:81], v[80:81], v[146:147]
	v_lshlrev_b32_e32 v144, 16, v178
	v_and_b32_e32 v145, 0xffff0000, v178
	v_lshlrev_b32_e32 v146, 16, v179
	v_and_b32_e32 v147, 0xffff0000, v179
	v_pk_add_f32 v[74:75], v[74:75], v[144:145]
	v_pk_add_f32 v[76:77], v[76:77], v[146:147]
	v_cvt_pk_bf16_f32 v176, v78, v79
	v_cvt_pk_bf16_f32 v177, v80, v81
	v_cvt_pk_bf16_f32 v178, v74, v75
	v_cvt_pk_bf16_f32 v179, v76, v77
	global_store_dwordx4 v139, v[176:179], s[34:35] sc1
	v_pk_mul_f32 v[78:79], v[78:79], v[78:79]
	v_pk_fma_f32 v[78:79], v[80:81], v[80:81], v[78:79]
	v_pk_fma_f32 v[78:79], v[74:75], v[74:75], v[78:79]
	v_pk_fma_f32 v[78:79], v[76:77], v[76:77], v[78:79]
	s_waitcnt vmcnt(15)
	v_lshlrev_b32_e32 v144, 16, v180
	v_and_b32_e32 v145, 0xffff0000, v180
	v_lshlrev_b32_e32 v146, 16, v181
	v_and_b32_e32 v147, 0xffff0000, v181
	v_pk_add_f32 v[70:71], v[70:71], v[144:145]
	v_pk_add_f32 v[72:73], v[72:73], v[146:147]
	v_lshlrev_b32_e32 v144, 16, v182
	v_and_b32_e32 v145, 0xffff0000, v182
	v_lshlrev_b32_e32 v146, 16, v183
	v_and_b32_e32 v147, 0xffff0000, v183
	v_pk_add_f32 v[66:67], v[66:67], v[144:145]
	v_pk_add_f32 v[68:69], v[68:69], v[146:147]
	v_cvt_pk_bf16_f32 v180, v70, v71
	v_cvt_pk_bf16_f32 v181, v72, v73
	v_cvt_pk_bf16_f32 v182, v66, v67
	v_cvt_pk_bf16_f32 v183, v68, v69
	global_store_dwordx4 v139, v[180:183], s[34:35] offset:256 sc1
	v_pk_fma_f32 v[78:79], v[70:71], v[70:71], v[78:79]
	v_pk_fma_f32 v[78:79], v[72:73], v[72:73], v[78:79]
	v_pk_fma_f32 v[78:79], v[66:67], v[66:67], v[78:79]
	v_pk_fma_f32 v[78:79], v[68:69], v[68:69], v[78:79]
	v_add_f32_e32 v78, v78, v79
	v_add_u32_e32 v139, 0x40000, v138
	s_waitcnt vmcnt(15)
	v_lshlrev_b32_e32 v144, 16, v184
	v_and_b32_e32 v145, 0xffff0000, v184
	v_lshlrev_b32_e32 v146, 16, v185
	v_and_b32_e32 v147, 0xffff0000, v185
	v_pk_add_f32 v[62:63], v[62:63], v[144:145]
	v_pk_add_f32 v[64:65], v[64:65], v[146:147]
	v_lshlrev_b32_e32 v144, 16, v186
	v_and_b32_e32 v145, 0xffff0000, v186
	v_lshlrev_b32_e32 v146, 16, v187
	v_and_b32_e32 v147, 0xffff0000, v187
	v_pk_add_f32 v[58:59], v[58:59], v[144:145]
	v_pk_add_f32 v[60:61], v[60:61], v[146:147]
	v_cvt_pk_bf16_f32 v184, v62, v63
	v_cvt_pk_bf16_f32 v185, v64, v65
	v_cvt_pk_bf16_f32 v186, v58, v59
	v_cvt_pk_bf16_f32 v187, v60, v61
	global_store_dwordx4 v139, v[184:187], s[34:35] sc1
	v_pk_mul_f32 v[62:63], v[62:63], v[62:63]
	v_pk_fma_f32 v[62:63], v[64:65], v[64:65], v[62:63]
	v_pk_fma_f32 v[62:63], v[58:59], v[58:59], v[62:63]
	v_pk_fma_f32 v[62:63], v[60:61], v[60:61], v[62:63]
	s_waitcnt vmcnt(15)
	v_lshlrev_b32_e32 v144, 16, v188
	v_and_b32_e32 v145, 0xffff0000, v188
	v_lshlrev_b32_e32 v146, 16, v189
	v_and_b32_e32 v147, 0xffff0000, v189
	v_pk_add_f32 v[54:55], v[54:55], v[144:145]
	v_pk_add_f32 v[56:57], v[56:57], v[146:147]
	v_lshlrev_b32_e32 v144, 16, v190
	v_and_b32_e32 v145, 0xffff0000, v190
	v_lshlrev_b32_e32 v146, 16, v191
	v_and_b32_e32 v147, 0xffff0000, v191
	v_pk_add_f32 v[50:51], v[50:51], v[144:145]
	v_pk_add_f32 v[52:53], v[52:53], v[146:147]
	v_cvt_pk_bf16_f32 v188, v54, v55
	v_cvt_pk_bf16_f32 v189, v56, v57
	v_cvt_pk_bf16_f32 v190, v50, v51
	v_cvt_pk_bf16_f32 v191, v52, v53
	global_store_dwordx4 v139, v[188:191], s[34:35] offset:256 sc1
	v_pk_fma_f32 v[62:63], v[54:55], v[54:55], v[62:63]
	v_pk_fma_f32 v[62:63], v[56:57], v[56:57], v[62:63]
	v_pk_fma_f32 v[62:63], v[50:51], v[50:51], v[62:63]
	v_pk_fma_f32 v[62:63], v[52:53], v[52:53], v[62:63]
	v_add_f32_e32 v62, v62, v63
	v_add_u32_e32 v139, 0x48000, v138
	s_waitcnt vmcnt(15)
	v_lshlrev_b32_e32 v144, 16, v192
	v_and_b32_e32 v145, 0xffff0000, v192
	v_lshlrev_b32_e32 v146, 16, v193
	v_and_b32_e32 v147, 0xffff0000, v193
	v_pk_add_f32 v[46:47], v[46:47], v[144:145]
	v_pk_add_f32 v[48:49], v[48:49], v[146:147]
	v_lshlrev_b32_e32 v144, 16, v194
	v_and_b32_e32 v145, 0xffff0000, v194
	v_lshlrev_b32_e32 v146, 16, v195
	v_and_b32_e32 v147, 0xffff0000, v195
	v_pk_add_f32 v[42:43], v[42:43], v[144:145]
	v_pk_add_f32 v[44:45], v[44:45], v[146:147]
	v_cvt_pk_bf16_f32 v192, v46, v47
	v_cvt_pk_bf16_f32 v193, v48, v49
	v_cvt_pk_bf16_f32 v194, v42, v43
	v_cvt_pk_bf16_f32 v195, v44, v45
	global_store_dwordx4 v139, v[192:195], s[34:35] sc1
	v_pk_mul_f32 v[46:47], v[46:47], v[46:47]
	v_pk_fma_f32 v[46:47], v[48:49], v[48:49], v[46:47]
	v_pk_fma_f32 v[46:47], v[42:43], v[42:43], v[46:47]
	v_pk_fma_f32 v[46:47], v[44:45], v[44:45], v[46:47]
	s_waitcnt vmcnt(15)
	v_lshlrev_b32_e32 v144, 16, v196
	v_and_b32_e32 v145, 0xffff0000, v196
	v_lshlrev_b32_e32 v146, 16, v197
	v_and_b32_e32 v147, 0xffff0000, v197
	v_pk_add_f32 v[38:39], v[38:39], v[144:145]
	v_pk_add_f32 v[40:41], v[40:41], v[146:147]
	v_lshlrev_b32_e32 v144, 16, v198
	v_and_b32_e32 v145, 0xffff0000, v198
	v_lshlrev_b32_e32 v146, 16, v199
	v_and_b32_e32 v147, 0xffff0000, v199
	v_pk_add_f32 v[34:35], v[34:35], v[144:145]
	v_pk_add_f32 v[36:37], v[36:37], v[146:147]
	v_cvt_pk_bf16_f32 v196, v38, v39
	v_cvt_pk_bf16_f32 v197, v40, v41
	v_cvt_pk_bf16_f32 v198, v34, v35
	v_cvt_pk_bf16_f32 v199, v36, v37
	global_store_dwordx4 v139, v[196:199], s[34:35] offset:256 sc1
	v_pk_fma_f32 v[46:47], v[38:39], v[38:39], v[46:47]
	v_pk_fma_f32 v[46:47], v[40:41], v[40:41], v[46:47]
	v_pk_fma_f32 v[46:47], v[34:35], v[34:35], v[46:47]
	v_pk_fma_f32 v[46:47], v[36:37], v[36:37], v[46:47]
	v_add_f32_e32 v46, v46, v47
	v_add_u32_e32 v139, 0x50000, v138
	s_waitcnt vmcnt(15)
; __device__ __forceinline__ float bflo(unsigned w) { return __uint_as_float(w << 16); }
; __device__ __forceinline__ float bfhi(unsigned w) { return __uint_as_float(w & 0xffff0000u); }
; __device__ __forceinline__ u32x4 pack8(const f32x4 a, const f32x4 b) { u32x4 w; w.x = cvt_pk_bf16(a[0], a[1]); w.y = cvt_pk_bf16(a[2], a[3]); w.z = cvt_pk_bf16(b[0], b[1]); w.w = cvt_pk_bf16(b[2], b[3]); return w; }
;     __device__ __forceinline__ void operator()(const f32x4 (&acc)[2][2][4][2], const Unit& u, int wr, int wc, int fr, int fq) const {
;         const int row0 = u.pm * 256 + wr * 64 + fr, col0 = u.pn * 256 + wc * 32 + 8 * fq;
; #pragma unroll
;         for (int ai = 0; ai < 2; ++ai)
; #pragma unroll
;             for (int m = 0; m < 4; ++m) {
;                 const int row = row0 + ai * 128 + m * 16; float p = 0.f;
; #pragma unroll
;                 for (int bj = 0; bj < 2; ++bj) {
;                     const size_t off = (size_t)row * D + col0 + bj * 128;
;                     const u32x4 xx = *(const u32x4*)(xb + off);
;                     const f32x4 x0 = (f32x4){bflo(xx.x), bfhi(xx.x), bflo(xx.y), bfhi(xx.y)}, x1 = (f32x4){bflo(xx.z), bfhi(xx.z), bflo(xx.w), bfhi(xx.w)};
;                     const f32x4 y0 = x0 + acc[ai][bj][m][0] * scale, y1 = x1 + acc[ai][bj][m][1] * scale;
;                     *(u32x4*)(xb + off) = pack8(y0, y1);
;                     const f32x4 q = y0 * y0 + y1 * y1; p += (q[0] + q[1]) + (q[2] + q[3]);
;                 }
;                 p += __shfl_xor(p, 16); p += __shfl_xor(p, 32);
;                 if (fq == 0) ssn[(size_t)row * 16 + u.pn * 4 + wc] = p;
;             }
	v_lshlrev_b32_e32 v144, 16, v200
	v_and_b32_e32 v145, 0xffff0000, v200
	v_lshlrev_b32_e32 v146, 16, v201
	v_and_b32_e32 v147, 0xffff0000, v201
	v_pk_add_f32 v[30:31], v[30:31], v[144:145]
	v_pk_add_f32 v[32:33], v[32:33], v[146:147]
	v_lshlrev_b32_e32 v144, 16, v202
	v_and_b32_e32 v145, 0xffff0000, v202
	v_lshlrev_b32_e32 v146, 16, v203
	v_and_b32_e32 v147, 0xffff0000, v203
	v_pk_add_f32 v[26:27], v[26:27], v[144:145]
	v_pk_add_f32 v[28:29], v[28:29], v[146:147]
	v_cvt_pk_bf16_f32 v200, v30, v31
	v_cvt_pk_bf16_f32 v201, v32, v33
	v_cvt_pk_bf16_f32 v202, v26, v27
	v_cvt_pk_bf16_f32 v203, v28, v29
	global_store_dwordx4 v139, v[200:203], s[34:35] sc1
	v_pk_mul_f32 v[30:31], v[30:31], v[30:31]
	v_pk_fma_f32 v[30:31], v[32:33], v[32:33], v[30:31]
	v_pk_fma_f32 v[30:31], v[26:27], v[26:27], v[30:31]
	v_pk_fma_f32 v[30:31], v[28:29], v[28:29], v[30:31]
	s_waitcnt vmcnt(15)
	v_lshlrev_b32_e32 v144, 16, v224
	v_and_b32_e32 v145, 0xffff0000, v224
	v_lshlrev_b32_e32 v146, 16, v225
	v_and_b32_e32 v147, 0xffff0000, v225
	v_pk_add_f32 v[22:23], v[22:23], v[144:145]
	v_pk_add_f32 v[24:25], v[24:25], v[146:147]
	v_lshlrev_b32_e32 v144, 16, v226
	v_and_b32_e32 v145, 0xffff0000, v226
	v_lshlrev_b32_e32 v146, 16, v227
	v_and_b32_e32 v147, 0xffff0000, v227
	v_pk_add_f32 v[18:19], v[18:19], v[144:145]
	v_pk_add_f32 v[20:21], v[20:21], v[146:147]
	v_cvt_pk_bf16_f32 v224, v22, v23
	v_cvt_pk_bf16_f32 v225, v24, v25
	v_cvt_pk_bf16_f32 v226, v18, v19
	v_cvt_pk_bf16_f32 v227, v20, v21
	global_store_dwordx4 v139, v[224:227], s[34:35] offset:256 sc1
	v_pk_fma_f32 v[30:31], v[22:23], v[22:23], v[30:31]
	v_pk_fma_f32 v[30:31], v[24:25], v[24:25], v[30:31]
	v_pk_fma_f32 v[30:31], v[18:19], v[18:19], v[30:31]
	v_pk_fma_f32 v[30:31], v[20:21], v[20:21], v[30:31]
	v_add_f32_e32 v30, v30, v31
	v_add_u32_e32 v139, 0x58000, v138
	s_waitcnt vmcnt(15)
	v_lshlrev_b32_e32 v144, 16, v228
	v_and_b32_e32 v145, 0xffff0000, v228
	v_lshlrev_b32_e32 v146, 16, v229
	v_and_b32_e32 v147, 0xffff0000, v229
	v_pk_add_f32 v[14:15], v[14:15], v[144:145]
	v_pk_add_f32 v[16:17], v[16:17], v[146:147]
	v_lshlrev_b32_e32 v144, 16, v230
	v_and_b32_e32 v145, 0xffff0000, v230
	v_lshlrev_b32_e32 v146, 16, v231
	v_and_b32_e32 v147, 0xffff0000, v231
	v_pk_add_f32 v[10:11], v[10:11], v[144:145]
	v_pk_add_f32 v[12:13], v[12:13], v[146:147]
	v_cvt_pk_bf16_f32 v228, v14, v15
	v_cvt_pk_bf16_f32 v229, v16, v17
	v_cvt_pk_bf16_f32 v230, v10, v11
	v_cvt_pk_bf16_f32 v231, v12, v13
	global_store_dwordx4 v139, v[228:231], s[34:35] sc1
	v_pk_mul_f32 v[14:15], v[14:15], v[14:15]
	v_pk_fma_f32 v[14:15], v[16:17], v[16:17], v[14:15]
	v_pk_fma_f32 v[14:15], v[10:11], v[10:11], v[14:15]
	v_pk_fma_f32 v[14:15], v[12:13], v[12:13], v[14:15]
	s_waitcnt vmcnt(15)
	v_lshlrev_b32_e32 v144, 16, v232
	v_and_b32_e32 v145, 0xffff0000, v232
	v_lshlrev_b32_e32 v146, 16, v233
	v_and_b32_e32 v147, 0xffff0000, v233
	v_pk_add_f32 v[6:7], v[6:7], v[144:145]
	v_pk_add_f32 v[8:9], v[8:9], v[146:147]
	v_lshlrev_b32_e32 v144, 16, v234
	v_and_b32_e32 v145, 0xffff0000, v234
	v_lshlrev_b32_e32 v146, 16, v235
	v_and_b32_e32 v147, 0xffff0000, v235
	v_pk_add_f32 v[2:3], v[2:3], v[144:145]
	v_pk_add_f32 v[4:5], v[4:5], v[146:147]
	v_cvt_pk_bf16_f32 v232, v6, v7
	v_cvt_pk_bf16_f32 v233, v8, v9
	v_cvt_pk_bf16_f32 v234, v2, v3
	v_cvt_pk_bf16_f32 v235, v4, v5
	global_store_dwordx4 v139, v[232:235], s[34:35] offset:256 sc1
	v_pk_fma_f32 v[14:15], v[6:7], v[6:7], v[14:15]
	v_pk_fma_f32 v[14:15], v[8:9], v[8:9], v[14:15]
	v_pk_fma_f32 v[14:15], v[2:3], v[2:3], v[14:15]
	v_pk_fma_f32 v[14:15], v[4:5], v[4:5], v[14:15]
	v_add_f32_e32 v14, v14, v15
	v_xor_b32_e32 v140, 16, v213
	v_xor_b32_e32 v141, 32, v213
	v_lshlrev_b32_e32 v140, 2, v140
	v_lshlrev_b32_e32 v141, 2, v141
	ds_bpermute_b32 v127, v140, v126
	ds_bpermute_b32 v111, v140, v110
	ds_bpermute_b32 v95, v140, v94
	ds_bpermute_b32 v79, v140, v78
	ds_bpermute_b32 v63, v140, v62
	ds_bpermute_b32 v47, v140, v46
	ds_bpermute_b32 v31, v140, v30
	ds_bpermute_b32 v15, v140, v14
	s_waitcnt lgkmcnt(0)
	v_add_f32_e32 v126, v126, v127
	v_add_f32_e32 v110, v110, v111
	v_add_f32_e32 v94, v94, v95
	v_add_f32_e32 v78, v78, v79
	v_add_f32_e32 v62, v62, v63
	v_add_f32_e32 v46, v46, v47
	v_add_f32_e32 v30, v30, v31
	v_add_f32_e32 v14, v14, v15
	ds_bpermute_b32 v127, v141, v126
	ds_bpermute_b32 v111, v141, v110
	ds_bpermute_b32 v95, v141, v94
	ds_bpermute_b32 v79, v141, v78
	ds_bpermute_b32 v63, v141, v62
	ds_bpermute_b32 v47, v141, v46
	ds_bpermute_b32 v31, v141, v30
	ds_bpermute_b32 v15, v141, v14
	s_waitcnt lgkmcnt(0)
	v_add_f32_e32 v126, v126, v127
	v_add_f32_e32 v110, v110, v111
	v_add_f32_e32 v94, v94, v95
	v_add_f32_e32 v78, v78, v79
	v_add_f32_e32 v62, v62, v63
	v_add_f32_e32 v46, v46, v47
	v_add_f32_e32 v30, v30, v31
	v_add_f32_e32 v14, v14, v15
	v_lshl_add_u32 v204, s20, 8, v148
	s_lshl_b32 s22, s18, 4
	s_lshl_b32 s23, s43, 2
	s_add_i32 s22, s22, s23
	v_lshlrev_b32_e32 v204, 6, v204
	v_add_u32_e32 v204, s22, v204
	v_add_u32_e32 v205, 0x2000, v204
	s_and_saveexec_b64 s[20:21], s[2:3]
	global_store_dword v204, v126, s[6:7] sc1
	global_store_dword v204, v110, s[6:7] offset:1024 sc1
	global_store_dword v204, v94, s[6:7] offset:2048 sc1
	global_store_dword v204, v78, s[6:7] offset:3072 sc1
	global_store_dword v205, v62, s[6:7] sc1
	global_store_dword v205, v46, s[6:7] offset:1024 sc1
	global_store_dword v205, v30, s[6:7] offset:2048 sc1
	global_store_dword v205, v14, s[6:7] offset:3072 sc1
	s_or_b64 exec, exec, s[20:21]
	s_andn2_b64 vcc, exec, s[4:5]
	s_mov_b64 s[4:5], -1
	s_cbranch_vccnz .LBB0_1042
	s_andn2_b64 vcc, exec, s[0:1]
	s_cbranch_vccnz .LBB0_1041
	s_barrier
	s_branch .LBB0_1041
